# u8 plus the same MFMA-stretch priority toggles in the peeled tail k-tiles after each GEMM loop
# speedup vs baseline: 1.0171x; 1.0037x over previous
; DI void gemm_128_deep(const bf16_t* __restrict__ A, int lda, const bf16_t* __restrict__ B, int ldb, int K, f32x16 (&acc)[2][2], bf16_t* sA, bf16_t* sBunused) {
;     ...
;   for (int k0 = 0; k0 < K - 256; k0 += 128) {
;     MMA_TILE(0)
;     ST_LDS(1, qa0, qa1, qa2, qa3, qb0, qb1, qb2, qb3)
;     GL_Q(k0 + 192)
;     __syncthreads();
;     MMA_TILE(1)
;     ST_LDS(0, pa0, pa1, pa2, pa3, pb0, pb1, pb2, pb3)
;     GL_P(k0 + 256)
;     __syncthreads();
;   }
.LBB0_208:
	ds_read_b128 v[168:171], v128
	ds_read_b128 v[172:175], v129 offset:18432
	ds_read_b128 v[176:179], v128 offset:32
	ds_read_b128 v[180:183], v129 offset:18464
	ds_read_b128 v[184:187], v129 offset:23040
	ds_read_b128 v[188:191], v129 offset:23072
	s_mov_b32 s45, 0x1304000
	s_waitcnt lgkmcnt(4)
	v_mfma_f32_32x32x16_bf16 v[48:63], v[168:171], v[172:175], v[48:63]
	s_mov_b32 s46, 0x1324000
	s_mov_b32 s47, 0x1344000
	s_mov_b32 s48, 0x1364000
	s_addk_i32 s43, 0x80
	s_cmpk_lt_u32 s43, 0x680
	s_waitcnt lgkmcnt(1)
	v_mfma_f32_32x32x16_bf16 v[32:47], v[168:171], v[184:187], v[32:47]
	ds_read_b128 v[168:171], v128 offset:4608
	ds_read_b128 v[192:195], v128 offset:4640
	s_waitcnt lgkmcnt(1)
	v_mfma_f32_32x32x16_bf16 v[16:31], v[168:171], v[172:175], v[16:31]
	v_mfma_f32_32x32x16_bf16 v[0:15], v[168:171], v[184:187], v[0:15]
	v_mfma_f32_32x32x16_bf16 v[48:63], v[176:179], v[180:183], v[48:63]
	v_mfma_f32_32x32x16_bf16 v[32:47], v[176:179], v[188:191], v[32:47]
	s_waitcnt lgkmcnt(0)
	v_mfma_f32_32x32x16_bf16 v[16:31], v[192:195], v[180:183], v[16:31]
	ds_read_b128 v[168:171], v129 offset:18496
	ds_read_b128 v[172:175], v128 offset:64
	ds_read_b128 v[176:179], v128 offset:96
	ds_read_b128 v[180:183], v128 offset:4672
	ds_read_b128 v[184:187], v128 offset:4704
	v_mfma_f32_32x32x16_bf16 v[0:15], v[192:195], v[188:191], v[0:15]
	ds_read_b128 v[188:191], v129 offset:18528
	ds_read_b128 v[192:195], v129 offset:23104
	ds_read_b128 v[196:199], v129 offset:23136
	s_setprio 0
	s_waitcnt vmcnt(15)
	ds_write_b128 v130, v[96:99] offset:36864
	s_waitcnt vmcnt(14)
	ds_write_b128 v130, v[100:103] offset:41472
	s_waitcnt vmcnt(13)
	ds_write_b128 v130, v[104:107] offset:46080
	s_waitcnt vmcnt(12)
	ds_write_b128 v130, v[108:111] offset:50688
	v_lshl_add_u64 v[96:97], v[150:151], 0, v[156:157]
	v_add_co_u32_e32 v152, vcc, s83, v96
	v_lshl_add_u64 v[98:99], v[148:149], 0, v[156:157]
	s_nop 0
	v_addc_co_u32_e32 v153, vcc, 0, v97, vcc
	v_add_co_u32_e32 v200, vcc, s84, v96
	s_waitcnt lgkmcnt(10)
	v_mfma_f32_32x32x16_bf16 v[48:63], v[172:175], v[168:171], v[48:63]
	v_addc_co_u32_e32 v201, vcc, 0, v97, vcc
	v_add_co_u32_e32 v202, vcc, s85, v96
	s_waitcnt vmcnt(11)
	ds_write_b128 v130, v[112:115] offset:55296
	s_waitcnt vmcnt(10)
	ds_write_b128 v130, v[116:119] offset:59904
	s_waitcnt vmcnt(9)
	ds_write_b128 v130, v[120:123] offset:64512
	s_waitcnt vmcnt(8)
	ds_write_b128 v131, v[124:127] offset:13824
	v_addc_co_u32_e32 v203, vcc, 0, v97, vcc
	s_waitcnt lgkmcnt(9)
	v_mfma_f32_32x32x16_bf16 v[32:47], v[172:175], v[192:195], v[32:47]
	v_add_co_u32_e32 v204, vcc, s86, v96
	v_lshl_add_u64 v[148:149], v[148:149], 0, s[94:95]
	s_nop 0
	v_addc_co_u32_e32 v205, vcc, 0, v97, vcc
	v_add_co_u32_e32 v206, vcc, s45, v98
	v_mfma_f32_32x32x16_bf16 v[16:31], v[180:183], v[168:171], v[16:31]
	s_nop 0
	v_addc_co_u32_e32 v207, vcc, 0, v99, vcc
	v_add_co_u32_e32 v208, vcc, s46, v98
	v_lshl_add_u64 v[150:151], v[150:151], 0, s[94:95]
	s_nop 0
	v_addc_co_u32_e32 v209, vcc, 0, v99, vcc
	v_mfma_f32_32x32x16_bf16 v[0:15], v[180:183], v[192:195], v[0:15]
	v_add_co_u32_e32 v210, vcc, s47, v98
	s_nop 1
	v_addc_co_u32_e32 v211, vcc, 0, v99, vcc
	v_add_co_u32_e32 v212, vcc, s48, v98
	v_mfma_f32_32x32x16_bf16 v[48:63], v[176:179], v[188:191], v[48:63]
	s_nop 0
	v_addc_co_u32_e32 v213, vcc, 0, v99, vcc
	global_load_dwordx4 v[96:99], v[152:153], off offset:2176
	global_load_dwordx4 v[100:103], v[200:201], off offset:2176
	global_load_dwordx4 v[104:107], v[202:203], off offset:2176
	global_load_dwordx4 v[108:111], v[204:205], off offset:2176
	global_load_dwordx4 v[112:115], v[206:207], off offset:2176
	global_load_dwordx4 v[116:119], v[208:209], off offset:2176
	global_load_dwordx4 v[120:123], v[210:211], off offset:2176
	global_load_dwordx4 v[124:127], v[212:213], off offset:2176
	s_waitcnt lgkmcnt(0)
	s_barrier
	s_setprio 1
	v_mfma_f32_32x32x16_bf16 v[32:47], v[176:179], v[196:199], v[32:47]
	ds_read_b128 v[168:171], v128 offset:36864
	ds_read_b128 v[172:175], v129 offset:55296
	ds_read_b128 v[176:179], v128 offset:36896
	ds_read_b128 v[180:183], v129 offset:55328
	v_mfma_f32_32x32x16_bf16 v[16:31], v[184:187], v[188:191], v[16:31]
	v_mfma_f32_32x32x16_bf16 v[0:15], v[184:187], v[196:199], v[0:15]
	ds_read_b128 v[184:187], v129 offset:59904
	ds_read_b128 v[188:191], v129 offset:59936
	s_waitcnt lgkmcnt(4)
	v_mfma_f32_32x32x16_bf16 v[48:63], v[168:171], v[172:175], v[48:63]
	s_waitcnt lgkmcnt(1)
	v_mfma_f32_32x32x16_bf16 v[32:47], v[168:171], v[184:187], v[32:47]
	ds_read_b128 v[168:171], v128 offset:41472
	ds_read_b128 v[192:195], v128 offset:41504
	s_waitcnt lgkmcnt(1)
	v_mfma_f32_32x32x16_bf16 v[16:31], v[168:171], v[172:175], v[16:31]
	v_mfma_f32_32x32x16_bf16 v[0:15], v[168:171], v[184:187], v[0:15]
	v_mfma_f32_32x32x16_bf16 v[48:63], v[176:179], v[180:183], v[48:63]
	v_mfma_f32_32x32x16_bf16 v[32:47], v[176:179], v[188:191], v[32:47]
	s_waitcnt lgkmcnt(0)
	v_mfma_f32_32x32x16_bf16 v[16:31], v[192:195], v[180:183], v[16:31]
	ds_read_b128 v[168:171], v128 offset:36928
	ds_read_b128 v[172:175], v129 offset:55360
	ds_read_b128 v[176:179], v128 offset:36960
	ds_read_b128 v[180:183], v129 offset:55392
	v_mfma_f32_32x32x16_bf16 v[0:15], v[192:195], v[188:191], v[0:15]
	ds_read_b128 v[184:187], v129 offset:59968
	ds_read_b128 v[188:191], v129 offset:60000
	s_waitcnt lgkmcnt(4)
	v_mfma_f32_32x32x16_bf16 v[48:63], v[168:171], v[172:175], v[48:63]
	s_waitcnt lgkmcnt(1)
	v_mfma_f32_32x32x16_bf16 v[32:47], v[168:171], v[184:187], v[32:47]
	ds_read_b128 v[168:171], v128 offset:41536
	ds_read_b128 v[192:195], v128 offset:41568
	s_setprio 0
	s_waitcnt vmcnt(13)
	ds_write_b128 v130, v[92:95]
	ds_write_b128 v130, v[64:67] offset:4608
	ds_write_b128 v130, v[68:71] offset:9216
	s_waitcnt vmcnt(11)
	ds_write_b128 v130, v[84:87] offset:13824
	ds_write_b128 v130, v[72:75] offset:18432
	s_waitcnt vmcnt(10)
	ds_write_b128 v130, v[76:79] offset:23040
	s_waitcnt vmcnt(9)
	ds_write_b128 v130, v[80:83] offset:27648
	s_waitcnt vmcnt(8)
	ds_write_b128 v130, v[88:91] offset:32256
	global_load_dwordx4 v[92:95], v[152:153], off offset:2304
	global_load_dwordx4 v[64:67], v[200:201], off offset:2304
	global_load_dwordx4 v[68:71], v[202:203], off offset:2304
	global_load_dwordx4 v[84:87], v[204:205], off offset:2304
	global_load_dwordx4 v[72:75], v[206:207], off offset:2304
	global_load_dwordx4 v[76:79], v[208:209], off offset:2304
	global_load_dwordx4 v[80:83], v[210:211], off offset:2304
	global_load_dwordx4 v[88:91], v[212:213], off offset:2304
	s_waitcnt lgkmcnt(0)
	s_barrier
; DI void gemm_128_deep(const bf16_t* __restrict__ A, int lda, const bf16_t* __restrict__ B, int ldb, int K, f32x16 (&acc)[2][2], bf16_t* sA, bf16_t* sBunused) {
;     ...
;   for (int k0 = 0; k0 < K - 256; k0 += 128) {
;     MMA_TILE(0)
;     ST_LDS(1, qa0, qa1, qa2, qa3, qb0, qb1, qb2, qb3)
;     GL_Q(k0 + 192)
;     __syncthreads();
;     MMA_TILE(1)
;     ST_LDS(0, pa0, pa1, pa2, pa3, pb0, pb1, pb2, pb3)
;     GL_P(k0 + 256)
;     __syncthreads();
;   }
;   MMA_TILE(0)
;   ST_LDS(1, qa0, qa1, qa2, qa3, qb0, qb1, qb2, qb3)
;   GL_Q(K - 64)
;   __syncthreads();
;   MMA_TILE(1)
;   ST_LDS(0, pa0, pa1, pa2, pa3, pb0, pb1, pb2, pb3)
;   __syncthreads();
;   MMA_TILE(0)
;   ST_LDS(1, qa0, qa1, qa2, qa3, qb0, qb1, qb2, qb3)
;   __syncthreads();
;   MMA_TILE(1)
;   __syncthreads();
	s_setprio 1
	v_mfma_f32_32x32x16_bf16 v[16:31], v[168:171], v[172:175], v[16:31]
	v_mfma_f32_32x32x16_bf16 v[0:15], v[168:171], v[184:187], v[0:15]
	v_mfma_f32_32x32x16_bf16 v[48:63], v[176:179], v[180:183], v[48:63]
	v_mfma_f32_32x32x16_bf16 v[32:47], v[176:179], v[188:191], v[32:47]
	v_mfma_f32_32x32x16_bf16 v[16:31], v[192:195], v[180:183], v[16:31]
	v_mfma_f32_32x32x16_bf16 v[0:15], v[192:195], v[188:191], v[0:15]
	s_cbranch_scc1 .LBB0_208
	ds_read_b128 v[148:151], v128
	ds_read_b128 v[168:171], v129 offset:18432
	ds_read_b128 v[172:175], v129 offset:23040
	s_mov_b64 s[52:53], -1
	s_cmp_gt_i32 s60, 15
	s_waitcnt lgkmcnt(1)
	v_mfma_f32_32x32x16_bf16 v[48:63], v[148:151], v[168:171], v[48:63]
	s_waitcnt lgkmcnt(0)
	v_mfma_f32_32x32x16_bf16 v[32:47], v[148:151], v[172:175], v[32:47]
	ds_read_b128 v[148:151], v128 offset:4608
	s_waitcnt lgkmcnt(0)
	v_mfma_f32_32x32x16_bf16 v[16:31], v[148:151], v[168:171], v[16:31]
	v_mfma_f32_32x32x16_bf16 v[0:15], v[148:151], v[172:175], v[0:15]
	ds_read_b128 v[148:151], v128 offset:32
	ds_read_b128 v[168:171], v129 offset:18464
	ds_read_b128 v[172:175], v129 offset:23072
	s_waitcnt lgkmcnt(1)
	v_mfma_f32_32x32x16_bf16 v[48:63], v[148:151], v[168:171], v[48:63]
	s_waitcnt lgkmcnt(0)
	v_mfma_f32_32x32x16_bf16 v[32:47], v[148:151], v[172:175], v[32:47]
	ds_read_b128 v[148:151], v128 offset:4640
	s_waitcnt lgkmcnt(0)
	v_mfma_f32_32x32x16_bf16 v[16:31], v[148:151], v[168:171], v[16:31]
	v_mfma_f32_32x32x16_bf16 v[0:15], v[148:151], v[172:175], v[0:15]
	ds_read_b128 v[148:151], v128 offset:64
	ds_read_b128 v[168:171], v129 offset:18496
	ds_read_b128 v[172:175], v129 offset:23104
	s_waitcnt lgkmcnt(1)
	v_mfma_f32_32x32x16_bf16 v[48:63], v[148:151], v[168:171], v[48:63]
	s_waitcnt lgkmcnt(0)
	v_mfma_f32_32x32x16_bf16 v[32:47], v[148:151], v[172:175], v[32:47]
	ds_read_b128 v[148:151], v128 offset:4672
	s_waitcnt lgkmcnt(0)
	v_mfma_f32_32x32x16_bf16 v[16:31], v[148:151], v[168:171], v[16:31]
	v_mfma_f32_32x32x16_bf16 v[0:15], v[148:151], v[172:175], v[0:15]
	ds_read_b128 v[148:151], v128 offset:96
	ds_read_b128 v[168:171], v129 offset:18528
	ds_read_b128 v[172:175], v129 offset:23136
	s_waitcnt lgkmcnt(1)
	v_mfma_f32_32x32x16_bf16 v[48:63], v[148:151], v[168:171], v[48:63]
	s_waitcnt lgkmcnt(0)
	v_mfma_f32_32x32x16_bf16 v[32:47], v[148:151], v[172:175], v[32:47]
	ds_read_b128 v[148:151], v128 offset:4704
	s_setprio 0
	s_waitcnt vmcnt(15)
	ds_write_b128 v130, v[96:99] offset:36864
	s_waitcnt vmcnt(14)
	ds_write_b128 v130, v[100:103] offset:41472
	s_waitcnt vmcnt(13)
	ds_write_b128 v130, v[104:107] offset:46080
	s_waitcnt vmcnt(12)
	ds_write_b128 v130, v[108:111] offset:50688
	s_waitcnt vmcnt(11)
	ds_write_b128 v130, v[112:115] offset:55296
	s_waitcnt vmcnt(10)
	ds_write_b128 v130, v[116:119] offset:59904
	s_waitcnt vmcnt(9)
	ds_write_b128 v130, v[120:123] offset:64512
	s_waitcnt vmcnt(8)
	ds_write_b128 v131, v[124:127] offset:13824
	global_load_dwordx4 v[96:99], v[142:143], off offset:3968
	global_load_dwordx4 v[100:103], v[138:139], off offset:3968
	global_load_dwordx4 v[104:107], v[144:145], off offset:3968
	global_load_dwordx4 v[108:111], v[146:147], off offset:3968
	global_load_dwordx4 v[112:115], v[132:133], off offset:3968
	global_load_dwordx4 v[116:119], v[134:135], off offset:3968
	global_load_dwordx4 v[120:123], v[136:137], off offset:3968
	global_load_dwordx4 v[124:127], v[140:141], off offset:3968
	s_waitcnt lgkmcnt(0)
	s_barrier
	s_setprio 1
	ds_read_b128 v[132:135], v128 offset:36864
	ds_read_b128 v[136:139], v129 offset:55296
	ds_read_b128 v[140:143], v129 offset:59904
	s_waitcnt lgkmcnt(1)
	v_mfma_f32_32x32x16_bf16 v[48:63], v[132:135], v[136:139], v[48:63]
	s_waitcnt lgkmcnt(0)
	v_mfma_f32_32x32x16_bf16 v[32:47], v[132:135], v[140:143], v[32:47]
	ds_read_b128 v[132:135], v128 offset:41472
	v_mfma_f32_32x32x16_bf16 v[16:31], v[148:151], v[168:171], v[16:31]
	v_mfma_f32_32x32x16_bf16 v[0:15], v[148:151], v[172:175], v[0:15]
	s_waitcnt lgkmcnt(0)
	v_mfma_f32_32x32x16_bf16 v[16:31], v[132:135], v[136:139], v[16:31]
	v_mfma_f32_32x32x16_bf16 v[0:15], v[132:135], v[140:143], v[0:15]
	ds_read_b128 v[132:135], v128 offset:36896
	ds_read_b128 v[136:139], v129 offset:55328
	ds_read_b128 v[140:143], v129 offset:59936
	s_waitcnt lgkmcnt(1)
	v_mfma_f32_32x32x16_bf16 v[48:63], v[132:135], v[136:139], v[48:63]
	s_waitcnt lgkmcnt(0)
	v_mfma_f32_32x32x16_bf16 v[32:47], v[132:135], v[140:143], v[32:47]
	ds_read_b128 v[132:135], v128 offset:41504
	s_waitcnt lgkmcnt(0)
	v_mfma_f32_32x32x16_bf16 v[16:31], v[132:135], v[136:139], v[16:31]
	v_mfma_f32_32x32x16_bf16 v[0:15], v[132:135], v[140:143], v[0:15]
	ds_read_b128 v[132:135], v128 offset:36928
	ds_read_b128 v[136:139], v129 offset:55360
	ds_read_b128 v[140:143], v129 offset:59968
	s_waitcnt lgkmcnt(1)
	v_mfma_f32_32x32x16_bf16 v[48:63], v[132:135], v[136:139], v[48:63]
	s_waitcnt lgkmcnt(0)
	v_mfma_f32_32x32x16_bf16 v[32:47], v[132:135], v[140:143], v[32:47]
	ds_read_b128 v[132:135], v128 offset:41536
	s_waitcnt lgkmcnt(0)
	v_mfma_f32_32x32x16_bf16 v[16:31], v[132:135], v[136:139], v[16:31]
	v_mfma_f32_32x32x16_bf16 v[0:15], v[132:135], v[140:143], v[0:15]
	ds_read_b128 v[132:135], v128 offset:36960
	ds_read_b128 v[136:139], v129 offset:55392
	ds_read_b128 v[140:143], v129 offset:60000
	s_waitcnt lgkmcnt(1)
	v_mfma_f32_32x32x16_bf16 v[48:63], v[132:135], v[136:139], v[48:63]
	s_waitcnt lgkmcnt(0)
	v_mfma_f32_32x32x16_bf16 v[32:47], v[132:135], v[140:143], v[32:47]
	ds_read_b128 v[132:135], v128 offset:41568
	s_setprio 0
	s_waitcnt vmcnt(15)
	ds_write_b128 v130, v[92:95]
	s_waitcnt vmcnt(14)
	ds_write_b128 v130, v[64:67] offset:4608
	s_waitcnt vmcnt(13)
	ds_write_b128 v130, v[68:71] offset:9216
	s_waitcnt vmcnt(12)
	ds_write_b128 v130, v[84:87] offset:13824
	s_waitcnt vmcnt(11)
	ds_write_b128 v130, v[72:75] offset:18432
	s_waitcnt vmcnt(10)
	ds_write_b128 v130, v[76:79] offset:23040
	s_waitcnt vmcnt(9)
	ds_write_b128 v130, v[80:83] offset:27648
	s_waitcnt vmcnt(8)
	ds_write_b128 v130, v[88:91] offset:32256
	s_waitcnt lgkmcnt(0)
	s_barrier
; DI void gemm_128_deep(const bf16_t* __restrict__ A, int lda, const bf16_t* __restrict__ B, int ldb, int K, f32x16 (&acc)[2][2], bf16_t* sA, bf16_t* sBunused) {
;     ...
;   MMA_TILE(0)
;   ST_LDS(1, qa0, qa1, qa2, qa3, qb0, qb1, qb2, qb3)
;   GL_Q(K - 64)
;   __syncthreads();
;   MMA_TILE(1)
;   ST_LDS(0, pa0, pa1, pa2, pa3, pb0, pb1, pb2, pb3)
;   __syncthreads();
;   MMA_TILE(0)
;   ST_LDS(1, qa0, qa1, qa2, qa3, qb0, qb1, qb2, qb3)
;   __syncthreads();
;   MMA_TILE(1)
;   __syncthreads();
	s_setprio 1
	ds_read_b128 v[64:67], v128
	ds_read_b128 v[68:71], v129 offset:18432
	ds_read_b128 v[72:75], v129 offset:23040
	s_waitcnt lgkmcnt(1)
	v_mfma_f32_32x32x16_bf16 v[48:63], v[64:67], v[68:71], v[48:63]
	s_waitcnt lgkmcnt(0)
	v_mfma_f32_32x32x16_bf16 v[32:47], v[64:67], v[72:75], v[32:47]
	ds_read_b128 v[64:67], v128 offset:4608
	v_mfma_f32_32x32x16_bf16 v[16:31], v[132:135], v[136:139], v[16:31]
	v_mfma_f32_32x32x16_bf16 v[0:15], v[132:135], v[140:143], v[0:15]
	s_waitcnt lgkmcnt(0)
	v_mfma_f32_32x32x16_bf16 v[16:31], v[64:67], v[68:71], v[16:31]
	v_mfma_f32_32x32x16_bf16 v[0:15], v[64:67], v[72:75], v[0:15]
	ds_read_b128 v[64:67], v128 offset:32
	ds_read_b128 v[68:71], v129 offset:18464
	ds_read_b128 v[72:75], v129 offset:23072
	s_waitcnt lgkmcnt(1)
	v_mfma_f32_32x32x16_bf16 v[48:63], v[64:67], v[68:71], v[48:63]
	s_waitcnt lgkmcnt(0)
	v_mfma_f32_32x32x16_bf16 v[32:47], v[64:67], v[72:75], v[32:47]
	ds_read_b128 v[64:67], v128 offset:4640
	s_waitcnt lgkmcnt(0)
	v_mfma_f32_32x32x16_bf16 v[16:31], v[64:67], v[68:71], v[16:31]
	v_mfma_f32_32x32x16_bf16 v[0:15], v[64:67], v[72:75], v[0:15]
	ds_read_b128 v[64:67], v128 offset:64
	ds_read_b128 v[68:71], v129 offset:18496
	ds_read_b128 v[72:75], v129 offset:23104
	s_waitcnt lgkmcnt(1)
	v_mfma_f32_32x32x16_bf16 v[48:63], v[64:67], v[68:71], v[48:63]
	s_waitcnt lgkmcnt(0)
	v_mfma_f32_32x32x16_bf16 v[32:47], v[64:67], v[72:75], v[32:47]
	ds_read_b128 v[64:67], v128 offset:4672
	s_waitcnt lgkmcnt(0)
	v_mfma_f32_32x32x16_bf16 v[16:31], v[64:67], v[68:71], v[16:31]
	v_mfma_f32_32x32x16_bf16 v[0:15], v[64:67], v[72:75], v[0:15]
	ds_read_b128 v[64:67], v128 offset:96
	ds_read_b128 v[68:71], v129 offset:18528
	ds_read_b128 v[72:75], v129 offset:23136
	s_waitcnt lgkmcnt(1)
	v_mfma_f32_32x32x16_bf16 v[48:63], v[64:67], v[68:71], v[48:63]
	s_waitcnt lgkmcnt(0)
	v_mfma_f32_32x32x16_bf16 v[32:47], v[64:67], v[72:75], v[32:47]
	ds_read_b128 v[64:67], v128 offset:4704
	s_setprio 0
	s_waitcnt vmcnt(7)
	ds_write_b128 v130, v[96:99] offset:36864
	s_waitcnt vmcnt(6)
	ds_write_b128 v130, v[100:103] offset:41472
	s_waitcnt vmcnt(5)
	ds_write_b128 v130, v[104:107] offset:46080
	s_waitcnt vmcnt(4)
	ds_write_b128 v130, v[108:111] offset:50688
	s_waitcnt vmcnt(3)
	ds_write_b128 v130, v[112:115] offset:55296
	s_waitcnt vmcnt(2)
	ds_write_b128 v130, v[116:119] offset:59904
	s_waitcnt vmcnt(1)
	ds_write_b128 v130, v[120:123] offset:64512
	s_waitcnt vmcnt(0)
	ds_write_b128 v131, v[124:127] offset:13824
	s_waitcnt lgkmcnt(0)
	s_barrier
	s_setprio 1
	v_mfma_f32_32x32x16_bf16 v[16:31], v[64:67], v[68:71], v[16:31]
	v_mfma_f32_32x32x16_bf16 v[0:15], v[64:67], v[72:75], v[0:15]
	ds_read_b128 v[64:67], v128 offset:36864
	ds_read_b128 v[68:71], v129 offset:55296
	ds_read_b128 v[72:75], v129 offset:59904
	s_waitcnt lgkmcnt(1)
	v_mfma_f32_32x32x16_bf16 v[48:63], v[64:67], v[68:71], v[48:63]
	s_waitcnt lgkmcnt(0)
	v_mfma_f32_32x32x16_bf16 v[32:47], v[64:67], v[72:75], v[32:47]
	ds_read_b128 v[64:67], v128 offset:41472
	s_waitcnt lgkmcnt(0)
	v_mfma_f32_32x32x16_bf16 v[16:31], v[64:67], v[68:71], v[16:31]
	v_mfma_f32_32x32x16_bf16 v[0:15], v[64:67], v[72:75], v[0:15]
	ds_read_b128 v[64:67], v128 offset:36896
	ds_read_b128 v[68:71], v129 offset:55328
	ds_read_b128 v[72:75], v129 offset:59936
	s_waitcnt lgkmcnt(1)
	v_mfma_f32_32x32x16_bf16 v[48:63], v[64:67], v[68:71], v[48:63]
	s_waitcnt lgkmcnt(0)
	v_mfma_f32_32x32x16_bf16 v[32:47], v[64:67], v[72:75], v[32:47]
	ds_read_b128 v[64:67], v128 offset:41504
	s_waitcnt lgkmcnt(0)
	v_mfma_f32_32x32x16_bf16 v[16:31], v[64:67], v[68:71], v[16:31]
	v_mfma_f32_32x32x16_bf16 v[0:15], v[64:67], v[72:75], v[0:15]
	ds_read_b128 v[64:67], v128 offset:36928
	ds_read_b128 v[68:71], v129 offset:55360
	ds_read_b128 v[72:75], v129 offset:59968
	s_waitcnt lgkmcnt(1)
	v_mfma_f32_32x32x16_bf16 v[48:63], v[64:67], v[68:71], v[48:63]
	s_waitcnt lgkmcnt(0)
	v_mfma_f32_32x32x16_bf16 v[32:47], v[64:67], v[72:75], v[32:47]
	ds_read_b128 v[64:67], v128 offset:41536
	s_waitcnt lgkmcnt(0)
	v_mfma_f32_32x32x16_bf16 v[16:31], v[64:67], v[68:71], v[16:31]
	v_mfma_f32_32x32x16_bf16 v[0:15], v[64:67], v[72:75], v[0:15]
	ds_read_b128 v[64:67], v128 offset:36960
	ds_read_b128 v[68:71], v129 offset:55392
	ds_read_b128 v[72:75], v129 offset:60000
	s_waitcnt lgkmcnt(1)
	v_mfma_f32_32x32x16_bf16 v[48:63], v[64:67], v[68:71], v[48:63]
	s_waitcnt lgkmcnt(0)
	v_mfma_f32_32x32x16_bf16 v[32:47], v[64:67], v[72:75], v[32:47]
	ds_read_b128 v[64:67], v128 offset:41568
	s_waitcnt lgkmcnt(0)
	s_barrier
	s_setprio 1
	v_mfma_f32_32x32x16_bf16 v[16:31], v[64:67], v[68:71], v[16:31]
	v_mfma_f32_32x32x16_bf16 v[0:15], v[64:67], v[72:75], v[0:15]
	s_setprio 0
	s_cbranch_scc1 .LBB0_213
	s_andn2_b64 vcc, exec, s[52:53]
	s_cbranch_vccz .LBB0_225

; DI void gemm_128_2set(const bf16_t* __restrict__ A, int lda, const bf16_t* __restrict__ B, int ldb, int K, f32x16 (&acc)[2][2], bf16_t* sA, bf16_t* sB) {
;     ...
;   for (int k0 = 0; k0 < K - 128; k0 += 128) {
;     __syncthreads();
;     ST2(pa0, pa1, pa2, pa3, pb0, pb1, pb2, pb3)
;     __syncthreads();
;     GL2_P(k0 + 128)
;     MMA2()
;     __syncthreads();
;     ST2(qa0, qa1, qa2, qa3, qb0, qb1, qb2, qb3)
;     __syncthreads();
;     GL2_Q(k0 + 192)
;     MMA2()
;   }
.LBB0_881:
	s_barrier
	s_setprio 1
	s_setprio 0
	s_waitcnt vmcnt(12)
	ds_write_b128 v184, v[108:111]
	ds_write_b128 v184, v[96:99] offset:4608
	ds_write_b128 v184, v[100:103] offset:9216
	ds_write_b128 v184, v[104:107] offset:13824
	s_waitcnt vmcnt(11)
	ds_write_b128 v184, v[112:115] offset:18432
	s_waitcnt vmcnt(10)
	ds_write_b128 v184, v[116:119] offset:23040
	s_waitcnt vmcnt(9)
	ds_write_b128 v184, v[120:123] offset:27648
	s_waitcnt vmcnt(8)
	ds_write_b128 v184, v[124:127] offset:32256
	s_waitcnt lgkmcnt(0)
	s_barrier
	s_setprio 1
	ds_read_b128 v[96:99], v128
	ds_read_b128 v[100:103], v129 offset:18432
	ds_read_b128 v[104:107], v128 offset:32
	ds_read_b128 v[108:111], v129 offset:18464
	ds_read_b128 v[112:115], v129 offset:23040
	ds_read_b128 v[116:119], v129 offset:23072
	s_waitcnt lgkmcnt(4)
	v_mfma_f32_32x32x16_bf16 v[48:63], v[96:99], v[100:103], v[48:63]
	s_mov_b32 s55, 0x19864000
	v_lshl_add_u64 v[202:203], v[130:131], 0, v[156:157]
	v_lshl_add_u64 v[204:205], v[138:139], 0, v[156:157]
	v_lshl_add_u64 v[206:207], v[134:135], 0, v[156:157]
	v_lshl_add_u64 v[208:209], v[136:137], 0, v[156:157]
	s_addk_i32 s54, 0x80
	v_lshl_add_u64 v[130:131], v[130:131], 0, s[94:95]
	s_waitcnt lgkmcnt(1)
	v_mfma_f32_32x32x16_bf16 v[32:47], v[96:99], v[112:115], v[32:47]
	ds_read_b128 v[96:99], v128 offset:4608
	ds_read_b128 v[120:123], v128 offset:4640
	v_lshl_add_u64 v[134:135], v[134:135], 0, s[94:95]
	v_lshl_add_u64 v[136:137], v[136:137], 0, s[94:95]
	s_cmpk_lt_u32 s54, 0x100
	v_lshl_add_u64 v[138:139], v[138:139], 0, s[94:95]
	s_waitcnt lgkmcnt(1)
	v_mfma_f32_32x32x16_bf16 v[16:31], v[96:99], v[100:103], v[16:31]
	v_mfma_f32_32x32x16_bf16 v[0:15], v[96:99], v[112:115], v[0:15]
	ds_read_b128 v[96:99], v128 offset:64
	ds_read_b128 v[100:103], v129 offset:18496
	ds_read_b128 v[186:189], v128 offset:96
	ds_read_b128 v[190:193], v129 offset:18528
	v_mfma_f32_32x32x16_bf16 v[48:63], v[104:107], v[108:111], v[48:63]
	v_mfma_f32_32x32x16_bf16 v[32:47], v[104:107], v[116:119], v[32:47]
	s_waitcnt lgkmcnt(4)
	v_mfma_f32_32x32x16_bf16 v[16:31], v[120:123], v[108:111], v[16:31]
	v_mfma_f32_32x32x16_bf16 v[0:15], v[120:123], v[116:119], v[0:15]
	ds_read_b128 v[112:115], v129 offset:23104
	ds_read_b128 v[116:119], v128 offset:4672
	ds_read_b128 v[194:197], v129 offset:23136
	ds_read_b128 v[198:201], v128 offset:4704
	v_lshl_add_u64 v[120:121], v[132:133], 0, v[156:157]
	v_add_co_u32_e32 v210, vcc, s55, v120
	s_mov_b32 s55, 0x1986c000
	s_nop 0
	v_addc_co_u32_e32 v211, vcc, 0, v121, vcc
	s_waitcnt lgkmcnt(6)
	v_mfma_f32_32x32x16_bf16 v[48:63], v[96:99], v[100:103], v[48:63]
	v_add_co_u32_e32 v212, vcc, s55, v120
	s_mov_b32 s55, 0x19874000
	s_nop 0
	v_addc_co_u32_e32 v213, vcc, 0, v121, vcc
	v_add_co_u32_e32 v226, vcc, s55, v120
	s_waitcnt lgkmcnt(3)
	v_mfma_f32_32x32x16_bf16 v[32:47], v[96:99], v[112:115], v[32:47]
	v_addc_co_u32_e32 v227, vcc, 0, v121, vcc
	s_mov_b32 s55, 0x1987c000
	v_add_co_u32_e32 v238, vcc, s55, v120
	global_load_dwordx4 v[108:111], v[202:203], off offset:256
	s_nop 0
	v_addc_co_u32_e32 v239, vcc, 0, v121, vcc
	s_waitcnt lgkmcnt(2)
	v_mfma_f32_32x32x16_bf16 v[16:31], v[116:119], v[100:103], v[16:31]
	global_load_dwordx4 v[96:99], v[204:205], off offset:256
	global_load_dwordx4 v[100:103], v[206:207], off offset:256
	global_load_dwordx4 v[104:107], v[208:209], off offset:256
	v_lshl_add_u64 v[132:133], v[132:133], 0, s[94:95]
	v_mfma_f32_32x32x16_bf16 v[0:15], v[116:119], v[112:115], v[0:15]
	global_load_dwordx4 v[112:115], v[210:211], off offset:2048
	global_load_dwordx4 v[116:119], v[212:213], off offset:2048
	global_load_dwordx4 v[120:123], v[226:227], off offset:2048
	global_load_dwordx4 v[124:127], v[238:239], off offset:2048
	s_waitcnt lgkmcnt(0)
	s_barrier
	s_setprio 1
	s_setprio 0
	s_waitcnt vmcnt(15)
	ds_write_b128 v184, v[64:67]
	s_waitcnt vmcnt(14)
	ds_write_b128 v184, v[68:71] offset:4608
	s_waitcnt vmcnt(13)
	ds_write_b128 v184, v[72:75] offset:9216
	s_waitcnt vmcnt(12)
	ds_write_b128 v184, v[80:83] offset:13824
	s_waitcnt vmcnt(11)
	ds_write_b128 v184, v[76:79] offset:18432
	s_waitcnt vmcnt(10)
	ds_write_b128 v184, v[84:87] offset:23040
	s_waitcnt vmcnt(9)
	ds_write_b128 v184, v[88:91] offset:27648
	s_waitcnt vmcnt(8)
	ds_write_b128 v184, v[92:95] offset:32256
	s_waitcnt lgkmcnt(0)
	v_mfma_f32_32x32x16_bf16 v[48:63], v[186:189], v[190:193], v[48:63]
	s_barrier
; DI void gemm_128_2set(const bf16_t* __restrict__ A, int lda, const bf16_t* __restrict__ B, int ldb, int K, f32x16 (&acc)[2][2], bf16_t* sA, bf16_t* sB) {
;     ...
;   __syncthreads();
;   ST2(pa0, pa1, pa2, pa3, pb0, pb1, pb2, pb3)
;   __syncthreads();
;   MMA2()
;   __syncthreads();
;   ST2(qa0, qa1, qa2, qa3, qb0, qb1, qb2, qb3)
;   __syncthreads();
;   MMA2()
	s_setprio 1
	ds_read_b128 v[64:67], v128
	ds_read_b128 v[68:71], v129 offset:18432
	ds_read_b128 v[72:75], v128 offset:32
	ds_read_b128 v[76:79], v129 offset:18464
	ds_read_b128 v[80:83], v129 offset:23040
	ds_read_b128 v[84:87], v129 offset:23072
	v_mfma_f32_32x32x16_bf16 v[32:47], v[186:189], v[194:197], v[32:47]
	v_mfma_f32_32x32x16_bf16 v[16:31], v[198:201], v[190:193], v[16:31]
	v_mfma_f32_32x32x16_bf16 v[0:15], v[198:201], v[194:197], v[0:15]
	s_waitcnt lgkmcnt(4)
	v_mfma_f32_32x32x16_bf16 v[48:63], v[64:67], v[68:71], v[48:63]
	s_waitcnt lgkmcnt(1)
	v_mfma_f32_32x32x16_bf16 v[32:47], v[64:67], v[80:83], v[32:47]
	ds_read_b128 v[64:67], v128 offset:4608
	ds_read_b128 v[88:91], v128 offset:4640
	s_waitcnt lgkmcnt(1)
	v_mfma_f32_32x32x16_bf16 v[16:31], v[64:67], v[68:71], v[16:31]
	v_mfma_f32_32x32x16_bf16 v[0:15], v[64:67], v[80:83], v[0:15]
	v_mfma_f32_32x32x16_bf16 v[48:63], v[72:75], v[76:79], v[48:63]
	v_mfma_f32_32x32x16_bf16 v[32:47], v[72:75], v[84:87], v[32:47]
	ds_read_b128 v[64:67], v128 offset:64
	ds_read_b128 v[68:71], v129 offset:18496
	ds_read_b128 v[72:75], v128 offset:96
	ds_read_b128 v[92:95], v129 offset:18528
	s_waitcnt lgkmcnt(4)
	v_mfma_f32_32x32x16_bf16 v[16:31], v[88:91], v[76:79], v[16:31]
	ds_read_b128 v[76:79], v129 offset:23104
	ds_read_b128 v[186:189], v129 offset:23136
	v_mfma_f32_32x32x16_bf16 v[0:15], v[88:91], v[84:87], v[0:15]
	s_waitcnt lgkmcnt(4)
	v_mfma_f32_32x32x16_bf16 v[48:63], v[64:67], v[68:71], v[48:63]
	s_waitcnt lgkmcnt(1)
	v_mfma_f32_32x32x16_bf16 v[32:47], v[64:67], v[76:79], v[32:47]
	ds_read_b128 v[64:67], v128 offset:4672
	ds_read_b128 v[190:193], v128 offset:4704
	s_waitcnt lgkmcnt(1)
	v_mfma_f32_32x32x16_bf16 v[16:31], v[64:67], v[68:71], v[16:31]
	v_mfma_f32_32x32x16_bf16 v[0:15], v[64:67], v[76:79], v[0:15]
	v_mfma_f32_32x32x16_bf16 v[48:63], v[72:75], v[92:95], v[48:63]
	v_mfma_f32_32x32x16_bf16 v[32:47], v[72:75], v[186:189], v[32:47]
	global_load_dwordx4 v[64:67], v[202:203], off offset:384
	global_load_dwordx4 v[68:71], v[204:205], off offset:384
	global_load_dwordx4 v[72:75], v[206:207], off offset:384
	global_load_dwordx4 v[80:83], v[208:209], off offset:384
	global_load_dwordx4 v[76:79], v[210:211], off offset:2176
	global_load_dwordx4 v[84:87], v[212:213], off offset:2176
	global_load_dwordx4 v[88:91], v[226:227], off offset:2176
	s_waitcnt lgkmcnt(0)
	v_mfma_f32_32x32x16_bf16 v[16:31], v[190:193], v[92:95], v[16:31]
	global_load_dwordx4 v[92:95], v[238:239], off offset:2176
	v_mfma_f32_32x32x16_bf16 v[0:15], v[190:193], v[186:189], v[0:15]
	s_cbranch_scc1 .LBB0_881
	s_barrier
	s_setprio 1
	s_setprio 0
	s_waitcnt vmcnt(15)
	ds_write_b128 v184, v[108:111]
	s_waitcnt vmcnt(14)
	ds_write_b128 v184, v[96:99] offset:4608
	s_waitcnt vmcnt(13)
	ds_write_b128 v184, v[100:103] offset:9216
	s_waitcnt vmcnt(12)
	ds_write_b128 v184, v[104:107] offset:13824
	s_waitcnt vmcnt(11)
	ds_write_b128 v184, v[112:115] offset:18432
	s_waitcnt vmcnt(10)
	ds_write_b128 v184, v[116:119] offset:23040
	s_waitcnt vmcnt(9)
	ds_write_b128 v184, v[120:123] offset:27648
	s_waitcnt vmcnt(8)
	ds_write_b128 v184, v[124:127] offset:32256
	s_waitcnt lgkmcnt(0)
	s_barrier
	s_setprio 1
	ds_read_b128 v[96:99], v128
	ds_read_b128 v[100:103], v129 offset:18432
	ds_read_b128 v[104:107], v128 offset:32
	ds_read_b128 v[108:111], v129 offset:18464
	ds_read_b128 v[112:115], v129 offset:23040
	ds_read_b128 v[116:119], v129 offset:23072
	s_waitcnt lgkmcnt(4)
	v_mfma_f32_32x32x16_bf16 v[48:63], v[96:99], v[100:103], v[48:63]
	s_lshl_b64 s[54:55], s[50:51], 12
	s_lshl_b64 s[52:53], s[52:53], 12
	s_add_u32 s52, s63, s52
	s_addc_u32 s53, s64, s53
	s_movk_i32 s51, 0xff80
	s_waitcnt lgkmcnt(1)
	v_mfma_f32_32x32x16_bf16 v[32:47], v[96:99], v[112:115], v[32:47]
	ds_read_b128 v[96:99], v128 offset:4608
	ds_read_b128 v[120:123], v128 offset:4640
	s_waitcnt lgkmcnt(1)
	v_mfma_f32_32x32x16_bf16 v[16:31], v[96:99], v[100:103], v[16:31]
	v_mfma_f32_32x32x16_bf16 v[0:15], v[96:99], v[112:115], v[0:15]
	v_mfma_f32_32x32x16_bf16 v[48:63], v[104:107], v[108:111], v[48:63]
	v_mfma_f32_32x32x16_bf16 v[32:47], v[104:107], v[116:119], v[32:47]
	s_waitcnt lgkmcnt(0)
	v_mfma_f32_32x32x16_bf16 v[16:31], v[120:123], v[108:111], v[16:31]
	ds_read_b128 v[96:99], v128 offset:64
	ds_read_b128 v[100:103], v129 offset:18496
	ds_read_b128 v[104:107], v128 offset:96
	ds_read_b128 v[108:111], v129 offset:18528
	v_mfma_f32_32x32x16_bf16 v[0:15], v[120:123], v[116:119], v[0:15]
	ds_read_b128 v[112:115], v129 offset:23104
	ds_read_b128 v[116:119], v129 offset:23136
	s_waitcnt lgkmcnt(4)
	v_mfma_f32_32x32x16_bf16 v[48:63], v[96:99], v[100:103], v[48:63]
	s_waitcnt lgkmcnt(1)
	v_mfma_f32_32x32x16_bf16 v[32:47], v[96:99], v[112:115], v[32:47]
	ds_read_b128 v[96:99], v128 offset:4672
	ds_read_b128 v[120:123], v128 offset:4704
	s_waitcnt lgkmcnt(0)
	s_barrier
	s_setprio 1
	s_setprio 0
	s_waitcnt vmcnt(7)
	ds_write_b128 v184, v[64:67]
	s_waitcnt vmcnt(6)
	ds_write_b128 v184, v[68:71] offset:4608
	s_waitcnt vmcnt(5)
	ds_write_b128 v184, v[72:75] offset:9216
	s_waitcnt vmcnt(4)
	ds_write_b128 v184, v[80:83] offset:13824
	s_waitcnt vmcnt(3)
	ds_write_b128 v184, v[76:79] offset:18432
	s_waitcnt vmcnt(2)
	ds_write_b128 v184, v[84:87] offset:23040
	s_waitcnt vmcnt(1)
	ds_write_b128 v184, v[88:91] offset:27648
	s_waitcnt vmcnt(0)
	ds_write_b128 v184, v[92:95] offset:32256
	s_waitcnt lgkmcnt(0)
	v_mfma_f32_32x32x16_bf16 v[16:31], v[96:99], v[100:103], v[16:31]
	s_barrier
; #define TIDX ltid()
; DI void gemm_128_2set(const bf16_t* __restrict__ A, int lda, const bf16_t* __restrict__ B, int ldb, int K, f32x16 (&acc)[2][2], bf16_t* sA, bf16_t* sB) {
;   const int tid = TIDX, lane = tid & 63, wid = tid >> 6, wm = wid >> 1, wn = wid & 1, r = lane & 31, h = lane >> 5;
;   const int lrow = tid >> 3, lkc = (tid & 7) * 8;
;   const bf16_t* ga = A + (size_t)lrow * lda + lkc;
;   const bf16_t* gb = B + (size_t)lrow * ldb + lkc;
;   uint4 pa0, pa1, pa2, pa3, pb0, pb1, pb2, pb3, qa0, qa1, qa2, qa3, qb0, qb1, qb2, qb3;
;     ...
;   GL2_P(0)
;   GL2_Q(64)
;     ...
;   MMA2()
;   __syncthreads();
;   ST2(qa0, qa1, qa2, qa3, qb0, qb1, qb2, qb3)
;   __syncthreads();
;   MMA2()
; DI void phase_merge(CP p, const Ptrs& w, int l, bf16_t* sA, bf16_t* sB, unsigned* sU) {
;     ...
; #pragma unroll
;         for (int a = 0; a < 2; ++a)
; #pragma unroll
;           for (int c = 0; c < 2; ++c)
; #pragma unroll
;             for (int i = 0; i < 8; ++i) sU[((a * 2 + c) * 8 + i) * 256 + tid] = pack2(U[a][c][2 * i], U[a][c][2 * i + 1]);
;       }
;       f32x16 G[2][2];
;       zero_acc(G);
;       gemm_128_2set(w.H + (size_t)m0 * 2048, 2048, gate_t + (size_t)(br * 2048 + n0) * 2048, 2048, 2048, G, sA, sB);
	s_setprio 1
	ds_read_b128 v[64:67], v128
	ds_read_b128 v[68:71], v129 offset:18432
	ds_read_b128 v[72:75], v128 offset:32
	ds_read_b128 v[76:79], v129 offset:18464
	ds_read_b128 v[80:83], v129 offset:23040
	ds_read_b128 v[84:87], v129 offset:23072
	v_mfma_f32_32x32x16_bf16 v[0:15], v[96:99], v[112:115], v[0:15]
	v_mfma_f32_32x32x16_bf16 v[48:63], v[104:107], v[108:111], v[48:63]
	v_mfma_f32_32x32x16_bf16 v[32:47], v[104:107], v[116:119], v[32:47]
	v_mfma_f32_32x32x16_bf16 v[16:31], v[120:123], v[108:111], v[16:31]
	v_mfma_f32_32x32x16_bf16 v[0:15], v[120:123], v[116:119], v[0:15]
	s_waitcnt lgkmcnt(4)
	v_mfma_f32_32x32x16_bf16 v[48:63], v[64:67], v[68:71], v[48:63]
	s_waitcnt lgkmcnt(1)
	v_mfma_f32_32x32x16_bf16 v[32:47], v[64:67], v[80:83], v[32:47]
	ds_read_b128 v[64:67], v128 offset:4608
	ds_read_b128 v[88:91], v128 offset:4640
	s_waitcnt lgkmcnt(1)
	v_mfma_f32_32x32x16_bf16 v[16:31], v[64:67], v[68:71], v[16:31]
	v_mfma_f32_32x32x16_bf16 v[0:15], v[64:67], v[80:83], v[0:15]
	v_mfma_f32_32x32x16_bf16 v[48:63], v[72:75], v[76:79], v[48:63]
	v_mfma_f32_32x32x16_bf16 v[32:47], v[72:75], v[84:87], v[32:47]
	s_waitcnt lgkmcnt(0)
	v_mfma_f32_32x32x16_bf16 v[16:31], v[88:91], v[76:79], v[16:31]
	ds_read_b128 v[64:67], v128 offset:64
	ds_read_b128 v[68:71], v129 offset:18496
	ds_read_b128 v[72:75], v128 offset:96
	ds_read_b128 v[76:79], v129 offset:18528
	v_mfma_f32_32x32x16_bf16 v[0:15], v[88:91], v[84:87], v[0:15]
	ds_read_b128 v[80:83], v129 offset:23104
	ds_read_b128 v[84:87], v128 offset:4672
	ds_read_b128 v[88:91], v128 offset:4704
	ds_read_b128 v[92:95], v129 offset:23136
	s_waitcnt lgkmcnt(6)
	v_mfma_f32_32x32x16_bf16 v[48:63], v[64:67], v[68:71], v[48:63]
	s_waitcnt lgkmcnt(3)
	v_mfma_f32_32x32x16_bf16 v[32:47], v[64:67], v[80:83], v[32:47]
	s_waitcnt lgkmcnt(2)
	v_mfma_f32_32x32x16_bf16 v[16:31], v[84:87], v[68:71], v[16:31]
	v_mfma_f32_32x32x16_bf16 v[0:15], v[84:87], v[80:83], v[0:15]
	v_mfma_f32_32x32x16_bf16 v[48:63], v[72:75], v[76:79], v[48:63]
	s_waitcnt lgkmcnt(0)
	v_mfma_f32_32x32x16_bf16 v[32:47], v[72:75], v[92:95], v[32:47]
	s_nop 9
	v_cvt_pk_bf16_f32 v48, v48, v49
	v_cvt_pk_bf16_f32 v49, v50, v51
	ds_write2st64_b32 v140, v48, v49 offset0:144 offset1:148
	v_cvt_pk_bf16_f32 v48, v52, v53
	v_cvt_pk_bf16_f32 v49, v54, v55
	ds_write2st64_b32 v140, v48, v49 offset0:152 offset1:156
	v_cvt_pk_bf16_f32 v48, v56, v57
	v_mfma_f32_32x32x16_bf16 v[16:31], v[88:91], v[76:79], v[16:31]
	v_cvt_pk_bf16_f32 v32, v32, v33
	v_cvt_pk_bf16_f32 v33, v34, v35
	ds_write2st64_b32 v140, v32, v33 offset0:176 offset1:180
	v_cvt_pk_bf16_f32 v32, v36, v37
	v_cvt_pk_bf16_f32 v33, v38, v39
	v_cvt_pk_bf16_f32 v49, v58, v59
	ds_write2st64_b32 v140, v32, v33 offset0:184 offset1:188
	v_mfma_f32_32x32x16_bf16 v[0:15], v[88:91], v[92:95], v[0:15]
	s_nop 3
	v_cvt_pk_bf16_f32 v16, v16, v17
	v_cvt_pk_bf16_f32 v17, v18, v19
	ds_write2st64_b32 v140, v16, v17 offset0:208 offset1:212
	v_cvt_pk_bf16_f32 v16, v20, v21
	v_cvt_pk_bf16_f32 v17, v22, v23
	v_cvt_pk_bf16_f32 v32, v40, v41
	v_cvt_pk_bf16_f32 v33, v42, v43
	s_nop 0
	v_cvt_pk_bf16_f32 v0, v0, v1
	v_cvt_pk_bf16_f32 v1, v2, v3
	ds_write2st64_b32 v140, v0, v1 offset0:240 offset1:244
	v_cvt_pk_bf16_f32 v0, v4, v5
	v_cvt_pk_bf16_f32 v1, v6, v7
	ds_write2st64_b32 v140, v16, v17 offset0:216 offset1:220
	v_cvt_pk_bf16_f32 v16, v24, v25
	v_cvt_pk_bf16_f32 v17, v26, v27
	ds_write2st64_b32 v140, v0, v1 offset0:248 offset1:252
	v_cvt_pk_bf16_f32 v0, v8, v9
	v_cvt_pk_bf16_f32 v1, v10, v11
	ds_write2st64_b32 v140, v48, v49 offset0:160 offset1:164
	v_cvt_pk_bf16_f32 v48, v60, v61
	v_cvt_pk_bf16_f32 v49, v62, v63
	ds_write2st64_b32 v140, v32, v33 offset0:192 offset1:196
	v_cvt_pk_bf16_f32 v32, v44, v45
	v_cvt_pk_bf16_f32 v33, v46, v47
	ds_write2st64_b32 v140, v16, v17 offset0:224 offset1:228
	v_cvt_pk_bf16_f32 v16, v28, v29
	v_cvt_pk_bf16_f32 v17, v30, v31
	ds_write2st64_b32 v141, v0, v1 offset0:112 offset1:116
	v_cvt_pk_bf16_f32 v0, v12, v13
	v_cvt_pk_bf16_f32 v1, v14, v15
	v_mov_b32_e32 v20, v214
	ds_write2st64_b32 v140, v48, v49 offset0:168 offset1:172
	ds_write2st64_b32 v140, v32, v33 offset0:200 offset1:204
	ds_write2st64_b32 v140, v16, v17 offset0:232 offset1:236
	ds_write2st64_b32 v141, v0, v1 offset0:120 offset1:124
	s_nop 0
	v_ashrrev_i32_e32 v0, 3, v20
	v_lshlrev_b32_e32 v1, 3, v20
	v_and_b32_e32 v6, 56, v1
	v_ashrrev_i32_e32 v1, 31, v0
	v_lshlrev_b64 v[2:3], 12, v[0:1]
	v_lshl_add_u64 v[4:5], s[40:41], 0, v[2:3]
	v_lshlrev_b32_e32 v156, 1, v6
	v_lshl_add_u64 v[4:5], v[4:5], 0, v[156:157]
	v_add_co_u32_e32 v8, vcc, s75, v4
	v_lshl_add_u64 v[6:7], s[52:53], 0, v[2:3]
	s_nop 0
	v_addc_co_u32_e32 v9, vcc, 0, v5, vcc
	v_add_co_u32_e32 v10, vcc, s80, v4
	v_lshl_add_u64 v[6:7], v[6:7], 0, v[156:157]
	s_nop 0
	v_addc_co_u32_e32 v11, vcc, 0, v5, vcc
	v_add_co_u32_e32 v12, vcc, s28, v4
	v_mul_lo_u32 v0, v0, s88
	s_nop 0
	v_addc_co_u32_e32 v13, vcc, 0, v5, vcc
	v_add_co_u32_e32 v14, vcc, s75, v6
	v_and_b32_e32 v1, 31, v20
	s_nop 0
	v_addc_co_u32_e32 v15, vcc, 0, v7, vcc
	v_add_co_u32_e32 v16, vcc, s80, v6
	v_lshl_add_u32 v134, v0, 1, v156
	s_nop 0
	v_addc_co_u32_e32 v17, vcc, 0, v7, vcc
	v_add_co_u32_e32 v18, vcc, s28, v6
	v_lshrrev_b32_e32 v0, 1, v20
	s_nop 0
	v_addc_co_u32_e32 v19, vcc, 0, v7, vcc
	global_load_dwordx4 v[96:99], v[4:5], off
	global_load_dwordx4 v[80:83], v[4:5], off offset:128
	global_load_dwordx4 v[100:103], v[8:9], off
	global_load_dwordx4 v[64:67], v[8:9], off offset:128
	global_load_dwordx4 v[104:107], v[10:11], off
	global_load_dwordx4 v[68:71], v[10:11], off offset:128
	global_load_dwordx4 v[108:111], v[12:13], off
	global_load_dwordx4 v[72:75], v[12:13], off offset:128
	global_load_dwordx4 v[112:115], v[6:7], off
; DI void gemm_128_2set(const bf16_t* __restrict__ A, int lda, const bf16_t* __restrict__ B, int ldb, int K, f32x16 (&acc)[2][2], bf16_t* sA, bf16_t* sB) {
;     ...
;   GL2_P(0)
;   GL2_Q(64)
;   for (int k0 = 0; k0 < K - 128; k0 += 128) {
;     __syncthreads();
;     ST2(pa0, pa1, pa2, pa3, pb0, pb1, pb2, pb3)
;     __syncthreads();
;     GL2_P(k0 + 128)
;     MMA2()
;     __syncthreads();
;     ST2(qa0, qa1, qa2, qa3, qb0, qb1, qb2, qb3)
;     __syncthreads();
;     GL2_Q(k0 + 192)
; DI void phase_merge(CP p, const Ptrs& w, int l, bf16_t* sA, bf16_t* sB, unsigned* sU) {
;     ...
;       f32x16 G[2][2];
;       zero_acc(G);
;       gemm_128_2set(w.H + (size_t)m0 * 2048, 2048, gate_t + (size_t)(br * 2048 + n0) * 2048, 2048, 2048, G, sA, sB);
	global_load_dwordx4 v[76:79], v[6:7], off offset:128
	global_load_dwordx4 v[116:119], v[14:15], off
	global_load_dwordx4 v[84:87], v[14:15], off offset:128
	global_load_dwordx4 v[120:123], v[16:17], off
	global_load_dwordx4 v[88:91], v[16:17], off offset:128
	global_load_dwordx4 v[124:127], v[18:19], off
	global_load_dwordx4 v[92:95], v[18:19], off offset:128
	v_and_or_b32 v1, v0, s82, v1
	v_and_b32_e32 v0, 16, v0
	v_mad_u64_u32 v[128:129], s[52:53], v1, s81, v[0:1]
	v_and_b32_e32 v1, 0x5f, v20
	v_mad_u32_u24 v129, v1, s81, v0
	v_and_b32_e32 v0, 7, v20
	s_add_u32 s52, s2, s54
	v_lshlrev_b32_e32 v156, 4, v0
	s_addc_u32 s53, s3, s55
	v_mov_b32_e32 v0, 0
	v_lshl_add_u64 v[130:131], s[52:53], 0, v[2:3]
	v_lshl_add_u64 v[132:133], s[48:49], 0, v[2:3]
	v_mov_b32_e32 v1, v0
	v_mov_b32_e32 v2, v0
	v_mov_b32_e32 v3, v0
	v_mov_b32_e32 v4, v0
	v_mov_b32_e32 v5, v0
	v_mov_b32_e32 v6, v0
	v_mov_b32_e32 v7, v0
	v_mov_b32_e32 v8, v0
	v_mov_b32_e32 v9, v0
	v_mov_b32_e32 v10, v0
	v_mov_b32_e32 v11, v0
	v_mov_b32_e32 v12, v0
	v_mov_b32_e32 v13, v0
	v_mov_b32_e32 v14, v0
	v_mov_b32_e32 v15, v0
	v_mov_b32_e32 v16, v0
	v_mov_b32_e32 v17, v0
	v_mov_b32_e32 v18, v0
	v_mov_b32_e32 v19, v0
	v_mov_b32_e32 v20, v0
	v_mov_b32_e32 v21, v0
	v_mov_b32_e32 v22, v0
	v_mov_b32_e32 v23, v0
	v_mov_b32_e32 v24, v0
	v_mov_b32_e32 v25, v0
	v_mov_b32_e32 v26, v0
	v_mov_b32_e32 v27, v0
	v_mov_b32_e32 v28, v0
	v_mov_b32_e32 v29, v0
	v_mov_b32_e32 v30, v0
	v_mov_b32_e32 v31, v0
	v_mov_b32_e32 v32, v0
	v_mov_b32_e32 v33, v0
	v_mov_b32_e32 v34, v0
	v_mov_b32_e32 v35, v0
	v_mov_b32_e32 v36, v0
	v_mov_b32_e32 v37, v0
	v_mov_b32_e32 v38, v0
	v_mov_b32_e32 v39, v0
	v_mov_b32_e32 v40, v0
	v_mov_b32_e32 v41, v0
	v_mov_b32_e32 v42, v0
	v_mov_b32_e32 v43, v0
	v_mov_b32_e32 v44, v0
	v_mov_b32_e32 v45, v0
	v_mov_b32_e32 v46, v0
	v_mov_b32_e32 v47, v0
	v_mov_b32_e32 v48, v0
	v_mov_b32_e32 v49, v0
	v_mov_b32_e32 v50, v0
	v_mov_b32_e32 v51, v0
	v_mov_b32_e32 v52, v0
	v_mov_b32_e32 v53, v0
	v_mov_b32_e32 v54, v0
	v_mov_b32_e32 v55, v0
	v_mov_b32_e32 v56, v0
	v_mov_b32_e32 v57, v0
	v_mov_b32_e32 v58, v0
	v_mov_b32_e32 v59, v0
	v_mov_b32_e32 v60, v0
	v_mov_b32_e32 v61, v0
	v_mov_b32_e32 v62, v0
	v_mov_b32_e32 v63, v0
	s_setprio 0
	s_waitcnt vmcnt(1)
.LBB0_883:
	s_waitcnt lgkmcnt(0)
	s_barrier
	s_setprio 1
	s_setprio 0
	s_waitcnt vmcnt(15)
	ds_write_b128 v134, v[96:99]
	s_waitcnt vmcnt(14)
	ds_write_b128 v134, v[100:103] offset:4608
	s_waitcnt vmcnt(13)
	ds_write_b128 v134, v[104:107] offset:9216
	s_waitcnt vmcnt(12)
	ds_write_b128 v134, v[108:111] offset:13824
	s_waitcnt vmcnt(11)
	ds_write_b128 v134, v[112:115] offset:18432
	s_waitcnt vmcnt(10)
	ds_write_b128 v134, v[116:119] offset:23040
	s_waitcnt vmcnt(9)
	ds_write_b128 v134, v[120:123] offset:27648
	s_waitcnt vmcnt(8)
	ds_write_b128 v134, v[124:127] offset:32256
	s_waitcnt lgkmcnt(0)
	s_barrier
	s_setprio 1
	ds_read_b128 v[96:99], v128
	ds_read_b128 v[100:103], v129 offset:18432
	ds_read_b128 v[104:107], v128 offset:32
	ds_read_b128 v[108:111], v129 offset:18464
	ds_read_b128 v[112:115], v129 offset:23040
	ds_read_b128 v[116:119], v129 offset:23072
	s_waitcnt lgkmcnt(4)
	v_mfma_f32_32x32x16_bf16 v[48:63], v[96:99], v[100:103], v[48:63]
	s_mov_b32 s52, 0x17864000
	s_addk_i32 s51, 0x80
	s_cmpk_lt_u32 s51, 0x700
	s_waitcnt lgkmcnt(1)
	v_mfma_f32_32x32x16_bf16 v[32:47], v[96:99], v[112:115], v[32:47]
	ds_read_b128 v[96:99], v128 offset:4608
	ds_read_b128 v[120:123], v128 offset:4640
	s_waitcnt lgkmcnt(1)
	v_mfma_f32_32x32x16_bf16 v[16:31], v[96:99], v[100:103], v[16:31]
	v_mfma_f32_32x32x16_bf16 v[0:15], v[96:99], v[112:115], v[0:15]
	v_lshl_add_u64 v[112:113], v[132:133], 0, v[156:157]
	ds_read_b128 v[96:99], v128 offset:4672
	ds_read_b128 v[100:103], v128 offset:64
	ds_read_b128 v[136:139], v128 offset:96
	v_add_co_u32_e32 v196, vcc, s83, v112
	v_lshl_add_u64 v[114:115], v[130:131], 0, v[156:157]
	s_nop 0
	v_addc_co_u32_e32 v197, vcc, 0, v113, vcc
	v_mfma_f32_32x32x16_bf16 v[48:63], v[104:107], v[108:111], v[48:63]
	v_add_co_u32_e32 v198, vcc, s84, v112
	v_lshl_add_u64 v[130:131], v[130:131], 0, s[94:95]
	s_nop 0
	v_addc_co_u32_e32 v199, vcc, 0, v113, vcc
	v_add_co_u32_e32 v200, vcc, s85, v112
	v_mfma_f32_32x32x16_bf16 v[32:47], v[104:107], v[116:119], v[32:47]
	s_nop 0
	v_addc_co_u32_e32 v201, vcc, 0, v113, vcc
	v_add_co_u32_e32 v202, vcc, s86, v112
	v_lshl_add_u64 v[132:133], v[132:133], 0, s[94:95]
	s_nop 0
	v_addc_co_u32_e32 v203, vcc, 0, v113, vcc
	s_waitcnt lgkmcnt(3)
	v_mfma_f32_32x32x16_bf16 v[16:31], v[120:123], v[108:111], v[16:31]
	ds_read_b128 v[184:187], v128 offset:4704
	ds_read_b128 v[104:107], v129 offset:18496
	ds_read_b128 v[188:191], v129 offset:18528
	ds_read_b128 v[108:111], v129 offset:23104
	ds_read_b128 v[192:195], v129 offset:23136
	v_add_co_u32_e32 v204, vcc, s52, v114
	s_mov_b32 s52, 0x17884000
	s_nop 0
	v_addc_co_u32_e32 v205, vcc, 0, v115, vcc
	v_add_co_u32_e32 v206, vcc, s52, v114
	v_mfma_f32_32x32x16_bf16 v[0:15], v[120:123], v[116:119], v[0:15]
	s_nop 0
	v_addc_co_u32_e32 v207, vcc, 0, v115, vcc
	s_mov_b32 s52, 0x178a4000
	v_add_co_u32_e32 v208, vcc, s52, v114
	s_mov_b32 s52, 0x178c4000
	s_nop 0
	v_addc_co_u32_e32 v209, vcc, 0, v115, vcc
	s_waitcnt lgkmcnt(3)
	v_mfma_f32_32x32x16_bf16 v[48:63], v[100:103], v[104:107], v[48:63]
	v_add_co_u32_e32 v210, vcc, s52, v114
	s_nop 1
	v_addc_co_u32_e32 v211, vcc, 0, v115, vcc
	s_waitcnt lgkmcnt(1)
	v_mfma_f32_32x32x16_bf16 v[32:47], v[100:103], v[108:111], v[32:47]
	v_mfma_f32_32x32x16_bf16 v[16:31], v[96:99], v[104:107], v[16:31]
	v_mfma_f32_32x32x16_bf16 v[0:15], v[96:99], v[108:111], v[0:15]
	global_load_dwordx4 v[96:99], v[196:197], off offset:2048
	global_load_dwordx4 v[100:103], v[198:199], off offset:2048
	global_load_dwordx4 v[104:107], v[200:201], off offset:2048
	global_load_dwordx4 v[108:111], v[202:203], off offset:2048
	global_load_dwordx4 v[112:115], v[204:205], off offset:2048
	global_load_dwordx4 v[116:119], v[206:207], off offset:2048
	global_load_dwordx4 v[120:123], v[208:209], off offset:2048
	global_load_dwordx4 v[124:127], v[210:211], off offset:2048
	s_waitcnt lgkmcnt(0)
	s_barrier
; DI void gemm_128_2set(const bf16_t* __restrict__ A, int lda, const bf16_t* __restrict__ B, int ldb, int K, f32x16 (&acc)[2][2], bf16_t* sA, bf16_t* sB) {
;     ...
;   for (int k0 = 0; k0 < K - 128; k0 += 128) {
;     __syncthreads();
;     ST2(pa0, pa1, pa2, pa3, pb0, pb1, pb2, pb3)
;     __syncthreads();
;     GL2_P(k0 + 128)
;     MMA2()
;     __syncthreads();
;     ST2(qa0, qa1, qa2, qa3, qb0, qb1, qb2, qb3)
;     __syncthreads();
;     GL2_Q(k0 + 192)
;     MMA2()
;   }
;   __syncthreads();
;   ST2(pa0, pa1, pa2, pa3, pb0, pb1, pb2, pb3)
;   __syncthreads();
;   MMA2()
;   __syncthreads();
;   ST2(qa0, qa1, qa2, qa3, qb0, qb1, qb2, qb3)
;   __syncthreads();
;   MMA2()
	s_setprio 1
	s_setprio 0
	s_waitcnt vmcnt(15)
	ds_write_b128 v134, v[80:83]
	s_waitcnt vmcnt(14)
	ds_write_b128 v134, v[64:67] offset:4608
	s_waitcnt vmcnt(13)
	ds_write_b128 v134, v[68:71] offset:9216
	s_waitcnt vmcnt(12)
	ds_write_b128 v134, v[72:75] offset:13824
	s_waitcnt vmcnt(11)
	ds_write_b128 v134, v[76:79] offset:18432
	s_waitcnt vmcnt(10)
	ds_write_b128 v134, v[84:87] offset:23040
	s_waitcnt vmcnt(9)
	ds_write_b128 v134, v[88:91] offset:27648
	s_waitcnt vmcnt(8)
	ds_write_b128 v134, v[92:95] offset:32256
	v_mfma_f32_32x32x16_bf16 v[48:63], v[136:139], v[188:191], v[48:63]
	s_waitcnt lgkmcnt(0)
	s_barrier
	s_setprio 1
	ds_read_b128 v[64:67], v128
	ds_read_b128 v[68:71], v129 offset:18432
	ds_read_b128 v[72:75], v128 offset:32
	ds_read_b128 v[76:79], v129 offset:18464
	ds_read_b128 v[80:83], v129 offset:23040
	ds_read_b128 v[84:87], v129 offset:23072
	v_mfma_f32_32x32x16_bf16 v[32:47], v[136:139], v[192:195], v[32:47]
	v_mfma_f32_32x32x16_bf16 v[16:31], v[184:187], v[188:191], v[16:31]
	v_mfma_f32_32x32x16_bf16 v[0:15], v[184:187], v[192:195], v[0:15]
	s_waitcnt lgkmcnt(4)
	v_mfma_f32_32x32x16_bf16 v[48:63], v[64:67], v[68:71], v[48:63]
	s_waitcnt lgkmcnt(1)
	v_mfma_f32_32x32x16_bf16 v[32:47], v[64:67], v[80:83], v[32:47]
	ds_read_b128 v[64:67], v128 offset:4608
	ds_read_b128 v[88:91], v128 offset:4640
	s_waitcnt lgkmcnt(1)
	v_mfma_f32_32x32x16_bf16 v[16:31], v[64:67], v[68:71], v[16:31]
	v_mfma_f32_32x32x16_bf16 v[0:15], v[64:67], v[80:83], v[0:15]
	v_mfma_f32_32x32x16_bf16 v[48:63], v[72:75], v[76:79], v[48:63]
	v_mfma_f32_32x32x16_bf16 v[32:47], v[72:75], v[84:87], v[32:47]
	ds_read_b128 v[64:67], v128 offset:64
	ds_read_b128 v[68:71], v129 offset:18496
	ds_read_b128 v[72:75], v128 offset:96
	ds_read_b128 v[92:95], v129 offset:18528
	s_waitcnt lgkmcnt(4)
	v_mfma_f32_32x32x16_bf16 v[16:31], v[88:91], v[76:79], v[16:31]
	ds_read_b128 v[76:79], v129 offset:23104
	ds_read_b128 v[136:139], v129 offset:23136
	v_mfma_f32_32x32x16_bf16 v[0:15], v[88:91], v[84:87], v[0:15]
	s_waitcnt lgkmcnt(4)
	v_mfma_f32_32x32x16_bf16 v[48:63], v[64:67], v[68:71], v[48:63]
	s_waitcnt lgkmcnt(1)
	v_mfma_f32_32x32x16_bf16 v[32:47], v[64:67], v[76:79], v[32:47]
	ds_read_b128 v[64:67], v128 offset:4672
	ds_read_b128 v[184:187], v128 offset:4704
	s_waitcnt lgkmcnt(1)
	v_mfma_f32_32x32x16_bf16 v[16:31], v[64:67], v[68:71], v[16:31]
	v_mfma_f32_32x32x16_bf16 v[0:15], v[64:67], v[76:79], v[0:15]
	v_mfma_f32_32x32x16_bf16 v[48:63], v[72:75], v[92:95], v[48:63]
	v_mfma_f32_32x32x16_bf16 v[32:47], v[72:75], v[136:139], v[32:47]
	global_load_dwordx4 v[80:83], v[196:197], off offset:2176
	global_load_dwordx4 v[64:67], v[198:199], off offset:2176
	global_load_dwordx4 v[68:71], v[200:201], off offset:2176
	global_load_dwordx4 v[72:75], v[202:203], off offset:2176
	global_load_dwordx4 v[76:79], v[204:205], off offset:2176
	global_load_dwordx4 v[84:87], v[206:207], off offset:2176
	global_load_dwordx4 v[88:91], v[208:209], off offset:2176
	s_waitcnt lgkmcnt(0)
	v_mfma_f32_32x32x16_bf16 v[16:31], v[184:187], v[92:95], v[16:31]
	global_load_dwordx4 v[92:95], v[210:211], off offset:2176
	v_mfma_f32_32x32x16_bf16 v[0:15], v[184:187], v[136:139], v[0:15]
	s_cbranch_scc1 .LBB0_883
	s_barrier
	s_setprio 1
	s_setprio 0
	s_waitcnt vmcnt(15)
	ds_write_b128 v134, v[96:99]
	s_waitcnt vmcnt(14)
	ds_write_b128 v134, v[100:103] offset:4608
	s_waitcnt vmcnt(13)
	ds_write_b128 v134, v[104:107] offset:9216
	s_waitcnt vmcnt(12)
	ds_write_b128 v134, v[108:111] offset:13824
	s_waitcnt vmcnt(11)
	ds_write_b128 v134, v[112:115] offset:18432
	s_waitcnt vmcnt(10)
	ds_write_b128 v134, v[116:119] offset:23040
	s_waitcnt vmcnt(9)
	ds_write_b128 v134, v[120:123] offset:27648
	s_waitcnt vmcnt(8)
	ds_write_b128 v134, v[124:127] offset:32256
	s_waitcnt lgkmcnt(0)
	s_barrier
	s_setprio 1
	ds_read_b128 v[96:99], v128 offset:4608
	ds_read_b128 v[100:103], v129 offset:23040
	ds_read_b128 v[104:107], v128
	ds_read_b128 v[108:111], v128 offset:32
	ds_read_b128 v[112:115], v129 offset:18432
	ds_read_b128 v[116:119], v129 offset:18464
	s_waitcnt lgkmcnt(1)
	v_mfma_f32_32x32x16_bf16 v[48:63], v[104:107], v[112:115], v[48:63]
	s_add_i32 s73, s73, 1
	s_addk_i32 s50, 0x800
	s_cmp_eq_u32 s73, 4
	v_mfma_f32_32x32x16_bf16 v[32:47], v[104:107], v[100:103], v[32:47]
	v_mfma_f32_32x32x16_bf16 v[16:31], v[96:99], v[112:115], v[16:31]
	v_mfma_f32_32x32x16_bf16 v[0:15], v[96:99], v[100:103], v[0:15]
	ds_read_b128 v[96:99], v128 offset:4640
	ds_read_b128 v[100:103], v129 offset:23072
	s_waitcnt lgkmcnt(2)
	v_mfma_f32_32x32x16_bf16 v[48:63], v[108:111], v[116:119], v[48:63]
	s_waitcnt lgkmcnt(0)
	v_mfma_f32_32x32x16_bf16 v[32:47], v[108:111], v[100:103], v[32:47]
	v_mfma_f32_32x32x16_bf16 v[16:31], v[96:99], v[116:119], v[16:31]
	v_mfma_f32_32x32x16_bf16 v[0:15], v[96:99], v[100:103], v[0:15]
	ds_read_b128 v[96:99], v128 offset:64
	ds_read_b128 v[100:103], v128 offset:4672
	ds_read_b128 v[104:107], v129 offset:18496
	ds_read_b128 v[108:111], v129 offset:23104
	s_waitcnt lgkmcnt(1)
	v_mfma_f32_32x32x16_bf16 v[48:63], v[96:99], v[104:107], v[48:63]
	s_waitcnt lgkmcnt(0)
	v_mfma_f32_32x32x16_bf16 v[32:47], v[96:99], v[108:111], v[32:47]
	v_mfma_f32_32x32x16_bf16 v[16:31], v[100:103], v[104:107], v[16:31]
	v_mfma_f32_32x32x16_bf16 v[0:15], v[100:103], v[108:111], v[0:15]
	ds_read_b128 v[96:99], v128 offset:96
	ds_read_b128 v[100:103], v128 offset:4704
	ds_read_b128 v[104:107], v129 offset:18528
	ds_read_b128 v[108:111], v129 offset:23136
	s_waitcnt lgkmcnt(0)
	s_barrier
; DI float sigmf(float x) { return __builtin_amdgcn_rcpf(1.f + __expf(-x)); }
; DI void gemm_128_2set(const bf16_t* __restrict__ A, int lda, const bf16_t* __restrict__ B, int ldb, int K, f32x16 (&acc)[2][2], bf16_t* sA, bf16_t* sB) {
;     ...
;   MMA2()
;   __syncthreads();
;   ST2(qa0, qa1, qa2, qa3, qb0, qb1, qb2, qb3)
;   __syncthreads();
;   MMA2()
; DI void phase_merge(CP p, const Ptrs& w, int l, bf16_t* sA, bf16_t* sB, unsigned* sU) {
;     ...
; #pragma unroll
;       for (int a = 0; a < 2; ++a)
; #pragma unroll
;         for (int c = 0; c < 2; ++c)
; #pragma unroll
;           for (int i = 0; i < 8; ++i) {
;             unsigned uv = sU[((a * 2 + c) * 8 + i) * 256 + tid];
;             float u0 = __uint_as_float(uv << 16), u1 = __uint_as_float(uv & 0xffff0000u);
;             const unsigned tv = totp[a][c][i];
;             float t0 = __uint_as_float(tv << 16) + sigmf(G[a][c][2 * i]) * u0;
;             float t1 = __uint_as_float(tv & 0xffff0000u) + sigmf(G[a][c][2 * i + 1]) * u1;
;             totp[a][c][i] = pack2(t0, t1);
;           }
	s_setprio 1
	s_setprio 0
	s_waitcnt vmcnt(7)
	ds_write_b128 v134, v[80:83]
	s_waitcnt vmcnt(6)
	ds_write_b128 v134, v[64:67] offset:4608
	s_waitcnt vmcnt(5)
	ds_write_b128 v134, v[68:71] offset:9216
	s_waitcnt vmcnt(4)
	ds_write_b128 v134, v[72:75] offset:13824
	s_waitcnt vmcnt(3)
	ds_write_b128 v134, v[76:79] offset:18432
	s_waitcnt vmcnt(2)
	ds_write_b128 v134, v[84:87] offset:23040
	s_waitcnt vmcnt(1)
	ds_write_b128 v134, v[88:91] offset:27648
	s_waitcnt vmcnt(0)
	ds_write_b128 v134, v[92:95] offset:32256
	s_waitcnt lgkmcnt(0)
	s_barrier
	s_setprio 1
	v_mfma_f32_32x32x16_bf16 v[48:63], v[96:99], v[104:107], v[48:63]
	ds_read_b128 v[64:67], v128 offset:4608
	ds_read_b128 v[68:71], v129 offset:23040
	ds_read_b128 v[72:75], v128
	ds_read_b128 v[76:79], v128 offset:32
	ds_read_b128 v[80:83], v129 offset:18432
	ds_read_b128 v[84:87], v129 offset:18464
	v_mfma_f32_32x32x16_bf16 v[32:47], v[96:99], v[108:111], v[32:47]
	v_mfma_f32_32x32x16_bf16 v[16:31], v[100:103], v[104:107], v[16:31]
	v_mfma_f32_32x32x16_bf16 v[0:15], v[100:103], v[108:111], v[0:15]
	s_waitcnt lgkmcnt(1)
	v_mfma_f32_32x32x16_bf16 v[48:63], v[72:75], v[80:83], v[48:63]
	v_mfma_f32_32x32x16_bf16 v[32:47], v[72:75], v[68:71], v[32:47]
	v_mfma_f32_32x32x16_bf16 v[16:31], v[64:67], v[80:83], v[16:31]
	v_mfma_f32_32x32x16_bf16 v[0:15], v[64:67], v[68:71], v[0:15]
	ds_read_b128 v[64:67], v128 offset:4640
	ds_read_b128 v[68:71], v129 offset:23072
	s_waitcnt lgkmcnt(2)
	v_mfma_f32_32x32x16_bf16 v[48:63], v[76:79], v[84:87], v[48:63]
	s_waitcnt lgkmcnt(0)
	v_mfma_f32_32x32x16_bf16 v[32:47], v[76:79], v[68:71], v[32:47]
	v_mfma_f32_32x32x16_bf16 v[16:31], v[64:67], v[84:87], v[16:31]
	v_mfma_f32_32x32x16_bf16 v[0:15], v[64:67], v[68:71], v[0:15]
	ds_read_b128 v[64:67], v128 offset:64
	ds_read_b128 v[68:71], v128 offset:4672
	ds_read_b128 v[72:75], v129 offset:18496
	ds_read_b128 v[76:79], v129 offset:23104
	s_waitcnt lgkmcnt(1)
	v_mfma_f32_32x32x16_bf16 v[48:63], v[64:67], v[72:75], v[48:63]
	s_waitcnt lgkmcnt(0)
	v_mfma_f32_32x32x16_bf16 v[32:47], v[64:67], v[76:79], v[32:47]
	v_mfma_f32_32x32x16_bf16 v[16:31], v[68:71], v[72:75], v[16:31]
	v_mfma_f32_32x32x16_bf16 v[0:15], v[68:71], v[76:79], v[0:15]
	ds_read_b128 v[64:67], v128 offset:96
	ds_read_b128 v[68:71], v128 offset:4704
	ds_read_b128 v[72:75], v129 offset:18528
	ds_read_b128 v[76:79], v129 offset:23136
	s_waitcnt lgkmcnt(1)
	v_mfma_f32_32x32x16_bf16 v[48:63], v[64:67], v[72:75], v[48:63]
	s_waitcnt lgkmcnt(0)
	v_mfma_f32_32x32x16_bf16 v[32:47], v[64:67], v[76:79], v[32:47]
	s_nop 9
	v_mul_f32_e32 v48, 0xbfb8aa3b, v48
	v_mul_f32_e32 v49, 0xbfb8aa3b, v49
	v_exp_f32_e32 v48, v48
	v_exp_f32_e32 v49, v49
	v_mul_f32_e32 v50, 0xbfb8aa3b, v50
	v_mul_f32_e32 v51, 0xbfb8aa3b, v51
	v_exp_f32_e32 v50, v50
	v_exp_f32_e32 v51, v51
	ds_read2st64_b32 v[64:65], v140 offset0:144 offset1:148
	v_add_f32_e32 v48, 1.0, v48
	v_add_f32_e32 v49, 1.0, v49
	v_rcp_f32_e32 v48, v48
	v_rcp_f32_e32 v49, v49
	v_add_f32_e32 v50, 1.0, v50
	v_add_f32_e32 v51, 1.0, v51
	v_rcp_f32_e32 v50, v50
	v_rcp_f32_e32 v51, v51
	v_mfma_f32_32x32x16_bf16 v[16:31], v[68:71], v[72:75], v[16:31]
	s_waitcnt lgkmcnt(0)
	v_lshlrev_b32_e32 v66, 16, v64
	v_and_b32_e32 v67, 0xffff0000, v64
	v_lshlrev_b32_e32 v64, 16, v182
	v_mul_f32_e32 v32, 0xbfb8aa3b, v32
	v_mul_f32_e32 v33, 0xbfb8aa3b, v33
	v_exp_f32_e32 v32, v32
	v_exp_f32_e32 v33, v33
	v_mfma_f32_32x32x16_bf16 v[0:15], v[68:71], v[76:79], v[0:15]
	s_setprio 0
	v_lshlrev_b32_e32 v68, 16, v183
	v_and_b32_e32 v69, 0xffff0000, v183
	v_fma_f32 v48, v48, v66, v68
	v_fma_f32 v49, v49, v67, v69
	v_mul_f32_e32 v34, 0xbfb8aa3b, v34
	v_cvt_pk_bf16_f32 v183, v48, v49
	v_lshlrev_b32_e32 v48, 16, v65
	v_and_b32_e32 v49, 0xffff0000, v65
	v_and_b32_e32 v65, 0xffff0000, v182
	v_pk_fma_f32 v[48:49], v[50:51], v[48:49], v[64:65]
	v_lshlrev_b32_e32 v64, 16, v181
	v_cvt_pk_bf16_f32 v182, v48, v49
	ds_read2st64_b32 v[48:49], v140 offset0:152 offset1:156
	v_and_b32_e32 v65, 0xffff0000, v181
	v_mul_f32_e32 v35, 0xbfb8aa3b, v35
	v_exp_f32_e32 v34, v34
	v_exp_f32_e32 v35, v35
	s_waitcnt lgkmcnt(0)
	v_lshlrev_b32_e32 v50, 16, v48
	v_and_b32_e32 v51, 0xffff0000, v48
	v_mul_f32_e32 v48, 0xbfb8aa3b, v52
	v_exp_f32_e32 v48, v48
	v_add_f32_e32 v32, 1.0, v32
	v_add_f32_e32 v33, 1.0, v33
	v_rcp_f32_e32 v32, v32
	v_add_f32_e32 v48, 1.0, v48
	v_rcp_f32_e32 v52, v48
	v_mul_f32_e32 v48, 0xbfb8aa3b, v53
	v_exp_f32_e32 v48, v48
	v_rcp_f32_e32 v33, v33
	v_add_f32_e32 v34, 1.0, v34
	v_add_f32_e32 v35, 1.0, v35
	v_add_f32_e32 v48, 1.0, v48
	v_rcp_f32_e32 v53, v48
	v_lshlrev_b32_e32 v48, 16, v49
	v_and_b32_e32 v49, 0xffff0000, v49
	v_rcp_f32_e32 v34, v34
	v_pk_fma_f32 v[50:51], v[52:53], v[50:51], v[64:65]
	v_mul_f32_e32 v53, 0xbfb8aa3b, v55
	v_cvt_pk_bf16_f32 v181, v50, v51
	v_mul_f32_e32 v51, 0xbfb8aa3b, v54
	v_exp_f32_e32 v51, v51
	v_exp_f32_e32 v53, v53
	v_lshlrev_b32_e32 v50, 16, v180
	v_rcp_f32_e32 v35, v35
	v_add_f32_e32 v51, 1.0, v51
	v_add_f32_e32 v53, 1.0, v53
	v_rcp_f32_e32 v52, v51
	v_rcp_f32_e32 v53, v53
	v_and_b32_e32 v51, 0xffff0000, v180
	v_mul_f32_e32 v16, 0xbfb8aa3b, v16
	v_mul_f32_e32 v17, 0xbfb8aa3b, v17
	v_pk_fma_f32 v[48:49], v[52:53], v[48:49], v[50:51]
	v_lshlrev_b32_e32 v52, 16, v179
	v_cvt_pk_bf16_f32 v180, v48, v49
	ds_read2st64_b32 v[48:49], v140 offset0:160 offset1:164
	v_and_b32_e32 v53, 0xffff0000, v179
	v_exp_f32_e32 v16, v16
	v_exp_f32_e32 v17, v17
	v_mul_f32_e32 v18, 0xbfb8aa3b, v18
	s_waitcnt lgkmcnt(0)
; DI float sigmf(float x) { return __builtin_amdgcn_rcpf(1.f + __expf(-x)); }
; DI void phase_merge(CP p, const Ptrs& w, int l, bf16_t* sA, bf16_t* sB, unsigned* sU) {
;     ...
; #pragma unroll
;       for (int a = 0; a < 2; ++a)
; #pragma unroll
;         for (int c = 0; c < 2; ++c)
; #pragma unroll
;           for (int i = 0; i < 8; ++i) {
;             unsigned uv = sU[((a * 2 + c) * 8 + i) * 256 + tid];
;             float u0 = __uint_as_float(uv << 16), u1 = __uint_as_float(uv & 0xffff0000u);
;             const unsigned tv = totp[a][c][i];
;             float t0 = __uint_as_float(tv << 16) + sigmf(G[a][c][2 * i]) * u0;
;             float t1 = __uint_as_float(tv & 0xffff0000u) + sigmf(G[a][c][2 * i + 1]) * u1;
;             totp[a][c][i] = pack2(t0, t1);
;           }
	v_lshlrev_b32_e32 v50, 16, v48
	v_and_b32_e32 v51, 0xffff0000, v48
	v_mul_f32_e32 v48, 0xbfb8aa3b, v56
	v_exp_f32_e32 v48, v48
	v_mul_f32_e32 v19, 0xbfb8aa3b, v19
	v_exp_f32_e32 v18, v18
	v_exp_f32_e32 v19, v19
	v_add_f32_e32 v48, 1.0, v48
	v_rcp_f32_e32 v54, v48
	v_mul_f32_e32 v48, 0xbfb8aa3b, v57
	v_exp_f32_e32 v48, v48
	v_add_f32_e32 v16, 1.0, v16
	v_add_f32_e32 v17, 1.0, v17
	v_rcp_f32_e32 v16, v16
	v_add_f32_e32 v48, 1.0, v48
	v_rcp_f32_e32 v55, v48
	v_lshlrev_b32_e32 v48, 16, v49
	v_and_b32_e32 v49, 0xffff0000, v49
	v_rcp_f32_e32 v17, v17
	v_pk_fma_f32 v[50:51], v[54:55], v[50:51], v[52:53]
	v_mul_f32_e32 v53, 0xbfb8aa3b, v59
	v_cvt_pk_bf16_f32 v179, v50, v51
	v_mul_f32_e32 v51, 0xbfb8aa3b, v58
	v_exp_f32_e32 v51, v51
	v_exp_f32_e32 v53, v53
	v_lshlrev_b32_e32 v50, 16, v177
	v_add_f32_e32 v18, 1.0, v18
	v_add_f32_e32 v51, 1.0, v51
	v_add_f32_e32 v53, 1.0, v53
	v_rcp_f32_e32 v52, v51
	v_rcp_f32_e32 v53, v53
	v_and_b32_e32 v51, 0xffff0000, v177
	v_add_f32_e32 v19, 1.0, v19
	v_rcp_f32_e32 v18, v18
	v_pk_fma_f32 v[48:49], v[52:53], v[48:49], v[50:51]
	v_lshlrev_b32_e32 v52, 16, v178
	v_cvt_pk_bf16_f32 v177, v48, v49
	ds_read2st64_b32 v[48:49], v140 offset0:168 offset1:172
	v_and_b32_e32 v53, 0xffff0000, v178
	v_rcp_f32_e32 v19, v19
	v_mul_f32_e32 v0, 0xbfb8aa3b, v0
	v_mul_f32_e32 v1, 0xbfb8aa3b, v1
	s_waitcnt lgkmcnt(0)
	v_lshlrev_b32_e32 v50, 16, v48
	v_and_b32_e32 v51, 0xffff0000, v48
	v_mul_f32_e32 v48, 0xbfb8aa3b, v60
	v_exp_f32_e32 v48, v48
	v_exp_f32_e32 v0, v0
	v_exp_f32_e32 v1, v1
	v_mul_f32_e32 v2, 0xbfb8aa3b, v2
	v_add_f32_e32 v48, 1.0, v48
	v_rcp_f32_e32 v54, v48
	v_mul_f32_e32 v48, 0xbfb8aa3b, v61
	v_exp_f32_e32 v48, v48
	v_mul_f32_e32 v3, 0xbfb8aa3b, v3
	v_exp_f32_e32 v2, v2
	v_exp_f32_e32 v3, v3
	v_add_f32_e32 v48, 1.0, v48
	v_rcp_f32_e32 v55, v48
	v_lshlrev_b32_e32 v48, 16, v49
	v_and_b32_e32 v49, 0xffff0000, v49
	v_add_f32_e32 v0, 1.0, v0
	v_pk_fma_f32 v[50:51], v[54:55], v[50:51], v[52:53]
	v_mul_f32_e32 v53, 0xbfb8aa3b, v63
	v_cvt_pk_bf16_f32 v178, v50, v51
	v_mul_f32_e32 v51, 0xbfb8aa3b, v62
	v_exp_f32_e32 v51, v51
	v_exp_f32_e32 v53, v53
	v_lshlrev_b32_e32 v50, 16, v173
	v_add_f32_e32 v1, 1.0, v1
	v_add_f32_e32 v51, 1.0, v51
	v_add_f32_e32 v53, 1.0, v53
	v_rcp_f32_e32 v52, v51
	v_rcp_f32_e32 v53, v53
	v_and_b32_e32 v51, 0xffff0000, v173
	v_rcp_f32_e32 v0, v0
	v_rcp_f32_e32 v1, v1
	v_pk_fma_f32 v[48:49], v[52:53], v[48:49], v[50:51]
	v_lshlrev_b32_e32 v52, 16, v176
	v_cvt_pk_bf16_f32 v173, v48, v49
	ds_read2st64_b32 v[48:49], v140 offset0:176 offset1:180
	v_and_b32_e32 v53, 0xffff0000, v176
	v_add_f32_e32 v2, 1.0, v2
	v_add_f32_e32 v3, 1.0, v3
	v_rcp_f32_e32 v2, v2
	s_waitcnt lgkmcnt(0)
	v_lshlrev_b32_e32 v50, 16, v48
	v_and_b32_e32 v51, 0xffff0000, v48
	v_pk_fma_f32 v[32:33], v[32:33], v[50:51], v[52:53]
	v_lshlrev_b32_e32 v48, 16, v170
	v_cvt_pk_bf16_f32 v176, v32, v33
	v_lshlrev_b32_e32 v32, 16, v49
	v_and_b32_e32 v33, 0xffff0000, v49
	v_and_b32_e32 v49, 0xffff0000, v170
	v_pk_fma_f32 v[32:33], v[34:35], v[32:33], v[48:49]
	v_lshlrev_b32_e32 v48, 16, v175
	v_cvt_pk_bf16_f32 v170, v32, v33
	ds_read2st64_b32 v[32:33], v140 offset0:184 offset1:188
	v_and_b32_e32 v49, 0xffff0000, v175
	v_rcp_f32_e32 v3, v3
	s_waitcnt lgkmcnt(0)
	v_lshlrev_b32_e32 v34, 16, v32
	v_and_b32_e32 v35, 0xffff0000, v32
	v_mul_f32_e32 v32, 0xbfb8aa3b, v36
	v_exp_f32_e32 v32, v32
	s_nop 0
	v_add_f32_e32 v32, 1.0, v32
	v_rcp_f32_e32 v36, v32
	v_mul_f32_e32 v32, 0xbfb8aa3b, v37
	v_exp_f32_e32 v32, v32
	s_nop 0
	v_add_f32_e32 v32, 1.0, v32
	v_rcp_f32_e32 v37, v32
	v_lshlrev_b32_e32 v32, 16, v33
	v_and_b32_e32 v33, 0xffff0000, v33
	v_pk_fma_f32 v[34:35], v[36:37], v[34:35], v[48:49]
	s_nop 0
	v_cvt_pk_bf16_f32 v175, v34, v35
	v_mul_f32_e32 v35, 0xbfb8aa3b, v38
	v_mul_f32_e32 v37, 0xbfb8aa3b, v39
	v_exp_f32_e32 v35, v35
	v_exp_f32_e32 v37, v37
	v_lshlrev_b32_e32 v34, 16, v174
	v_add_f32_e32 v35, 1.0, v35
	v_add_f32_e32 v37, 1.0, v37
	v_rcp_f32_e32 v36, v35
	v_rcp_f32_e32 v37, v37
	v_and_b32_e32 v35, 0xffff0000, v174
	v_pk_fma_f32 v[32:33], v[36:37], v[32:33], v[34:35]
	s_nop 0
	v_cvt_pk_bf16_f32 v174, v32, v33
	ds_read2st64_b32 v[32:33], v140 offset0:192 offset1:196
	v_lshlrev_b32_e32 v36, 16, v172
	v_and_b32_e32 v37, 0xffff0000, v172
	s_waitcnt lgkmcnt(0)
	v_lshlrev_b32_e32 v34, 16, v32
	v_and_b32_e32 v35, 0xffff0000, v32
	v_mul_f32_e32 v32, 0xbfb8aa3b, v40
	v_exp_f32_e32 v32, v32
	s_nop 0
	v_add_f32_e32 v32, 1.0, v32
	v_rcp_f32_e32 v38, v32
	v_mul_f32_e32 v32, 0xbfb8aa3b, v41
	v_exp_f32_e32 v32, v32
	s_nop 0
	v_add_f32_e32 v32, 1.0, v32
	v_rcp_f32_e32 v39, v32
	v_lshlrev_b32_e32 v32, 16, v33
	v_and_b32_e32 v33, 0xffff0000, v33
	v_pk_fma_f32 v[34:35], v[38:39], v[34:35], v[36:37]
	s_nop 0
	v_cvt_pk_bf16_f32 v172, v34, v35
	v_mul_f32_e32 v35, 0xbfb8aa3b, v42
	v_mul_f32_e32 v37, 0xbfb8aa3b, v43
	v_exp_f32_e32 v35, v35
	v_exp_f32_e32 v37, v37
	v_lshlrev_b32_e32 v34, 16, v171
	v_add_f32_e32 v35, 1.0, v35
	v_add_f32_e32 v37, 1.0, v37
	v_rcp_f32_e32 v36, v35
	v_rcp_f32_e32 v37, v37
	v_and_b32_e32 v35, 0xffff0000, v171
	v_pk_fma_f32 v[32:33], v[36:37], v[32:33], v[34:35]
	s_nop 0
	v_cvt_pk_bf16_f32 v171, v32, v33
	ds_read2st64_b32 v[32:33], v140 offset0:200 offset1:204
	v_lshlrev_b32_e32 v36, 16, v169
	v_and_b32_e32 v37, 0xffff0000, v169
	s_waitcnt lgkmcnt(0)
; DI float sigmf(float x) { return __builtin_amdgcn_rcpf(1.f + __expf(-x)); }
; DI void phase_merge(CP p, const Ptrs& w, int l, bf16_t* sA, bf16_t* sB, unsigned* sU) {
;     ...
; #pragma unroll
;       for (int a = 0; a < 2; ++a)
; #pragma unroll
;         for (int c = 0; c < 2; ++c)
; #pragma unroll
;           for (int i = 0; i < 8; ++i) {
;             unsigned uv = sU[((a * 2 + c) * 8 + i) * 256 + tid];
;             float u0 = __uint_as_float(uv << 16), u1 = __uint_as_float(uv & 0xffff0000u);
;             const unsigned tv = totp[a][c][i];
;             float t0 = __uint_as_float(tv << 16) + sigmf(G[a][c][2 * i]) * u0;
;             float t1 = __uint_as_float(tv & 0xffff0000u) + sigmf(G[a][c][2 * i + 1]) * u1;
;             totp[a][c][i] = pack2(t0, t1);
;           }
	v_lshlrev_b32_e32 v34, 16, v32
	v_and_b32_e32 v35, 0xffff0000, v32
	v_mul_f32_e32 v32, 0xbfb8aa3b, v44
	v_exp_f32_e32 v32, v32
	s_nop 0
	v_add_f32_e32 v32, 1.0, v32
	v_rcp_f32_e32 v38, v32
	v_mul_f32_e32 v32, 0xbfb8aa3b, v45
	v_exp_f32_e32 v32, v32
	s_nop 0
	v_add_f32_e32 v32, 1.0, v32
	v_rcp_f32_e32 v39, v32
	v_lshlrev_b32_e32 v32, 16, v33
	v_and_b32_e32 v33, 0xffff0000, v33
	v_pk_fma_f32 v[34:35], v[38:39], v[34:35], v[36:37]
	s_nop 0
	v_cvt_pk_bf16_f32 v169, v34, v35
	v_mul_f32_e32 v35, 0xbfb8aa3b, v46
	v_mul_f32_e32 v37, 0xbfb8aa3b, v47
	v_exp_f32_e32 v35, v35
	v_exp_f32_e32 v37, v37
	v_lshlrev_b32_e32 v34, 16, v168
	v_add_f32_e32 v35, 1.0, v35
	v_add_f32_e32 v37, 1.0, v37
	v_rcp_f32_e32 v36, v35
	v_rcp_f32_e32 v37, v37
	v_and_b32_e32 v35, 0xffff0000, v168
	v_pk_fma_f32 v[32:33], v[36:37], v[32:33], v[34:35]
	s_nop 0
	v_cvt_pk_bf16_f32 v168, v32, v33
	ds_read2st64_b32 v[32:33], v140 offset0:208 offset1:212
	v_lshlrev_b32_e32 v36, 16, v167
	v_and_b32_e32 v37, 0xffff0000, v167
	s_waitcnt lgkmcnt(0)
	v_lshlrev_b32_e32 v34, 16, v32
	v_and_b32_e32 v35, 0xffff0000, v32
	v_pk_fma_f32 v[16:17], v[16:17], v[34:35], v[36:37]
	v_lshlrev_b32_e32 v32, 16, v164
	v_cvt_pk_bf16_f32 v167, v16, v17
	v_lshlrev_b32_e32 v16, 16, v33
	v_and_b32_e32 v17, 0xffff0000, v33
	v_and_b32_e32 v33, 0xffff0000, v164
	v_pk_fma_f32 v[16:17], v[18:19], v[16:17], v[32:33]
	v_lshlrev_b32_e32 v32, 16, v163
	v_cvt_pk_bf16_f32 v164, v16, v17
	ds_read2st64_b32 v[16:17], v140 offset0:216 offset1:220
	v_and_b32_e32 v33, 0xffff0000, v163
	s_waitcnt lgkmcnt(0)
	v_lshlrev_b32_e32 v18, 16, v16
	v_and_b32_e32 v19, 0xffff0000, v16
	v_mul_f32_e32 v16, 0xbfb8aa3b, v20
	v_exp_f32_e32 v16, v16
	s_nop 0
	v_add_f32_e32 v16, 1.0, v16
	v_rcp_f32_e32 v20, v16
	v_mul_f32_e32 v16, 0xbfb8aa3b, v21
	v_exp_f32_e32 v16, v16
	s_nop 0
	v_add_f32_e32 v16, 1.0, v16
	v_rcp_f32_e32 v21, v16
	v_lshlrev_b32_e32 v16, 16, v17
	v_and_b32_e32 v17, 0xffff0000, v17
	v_pk_fma_f32 v[18:19], v[20:21], v[18:19], v[32:33]
	s_nop 0
	v_cvt_pk_bf16_f32 v163, v18, v19
	v_mul_f32_e32 v19, 0xbfb8aa3b, v22
	v_mul_f32_e32 v21, 0xbfb8aa3b, v23
	v_exp_f32_e32 v19, v19
	v_exp_f32_e32 v21, v21
	v_lshlrev_b32_e32 v18, 16, v161
	v_add_f32_e32 v19, 1.0, v19
	v_add_f32_e32 v21, 1.0, v21
	v_rcp_f32_e32 v20, v19
	v_rcp_f32_e32 v21, v21
	v_and_b32_e32 v19, 0xffff0000, v161
	v_pk_fma_f32 v[16:17], v[20:21], v[16:17], v[18:19]
	s_nop 0
	v_cvt_pk_bf16_f32 v161, v16, v17
	ds_read2st64_b32 v[16:17], v140 offset0:224 offset1:228
	v_lshlrev_b32_e32 v20, 16, v155
	v_and_b32_e32 v21, 0xffff0000, v155
	s_waitcnt lgkmcnt(0)
	v_lshlrev_b32_e32 v18, 16, v16
	v_and_b32_e32 v19, 0xffff0000, v16
	v_mul_f32_e32 v16, 0xbfb8aa3b, v24
	v_exp_f32_e32 v16, v16
	s_nop 0
	v_add_f32_e32 v16, 1.0, v16
	v_rcp_f32_e32 v22, v16
	v_mul_f32_e32 v16, 0xbfb8aa3b, v25
	v_exp_f32_e32 v16, v16
	s_nop 0
	v_add_f32_e32 v16, 1.0, v16
	v_rcp_f32_e32 v23, v16
	v_lshlrev_b32_e32 v16, 16, v17
	v_and_b32_e32 v17, 0xffff0000, v17
	v_pk_fma_f32 v[18:19], v[22:23], v[18:19], v[20:21]
	s_nop 0
	v_cvt_pk_bf16_f32 v155, v18, v19
	v_mul_f32_e32 v19, 0xbfb8aa3b, v26
	v_mul_f32_e32 v21, 0xbfb8aa3b, v27
	v_exp_f32_e32 v19, v19
	v_exp_f32_e32 v21, v21
	v_lshlrev_b32_e32 v18, 16, v154
	v_add_f32_e32 v19, 1.0, v19
	v_add_f32_e32 v21, 1.0, v21
	v_rcp_f32_e32 v20, v19
	v_rcp_f32_e32 v21, v21
	v_and_b32_e32 v19, 0xffff0000, v154
	v_pk_fma_f32 v[16:17], v[20:21], v[16:17], v[18:19]
	s_nop 0
	v_cvt_pk_bf16_f32 v154, v16, v17
	ds_read2st64_b32 v[16:17], v140 offset0:232 offset1:236
	v_lshlrev_b32_e32 v20, 16, v153
	v_and_b32_e32 v21, 0xffff0000, v153
	s_waitcnt lgkmcnt(0)
	v_lshlrev_b32_e32 v18, 16, v16
	v_and_b32_e32 v19, 0xffff0000, v16
	v_mul_f32_e32 v16, 0xbfb8aa3b, v28
	v_exp_f32_e32 v16, v16
	s_nop 0
	v_add_f32_e32 v16, 1.0, v16
	v_rcp_f32_e32 v22, v16
	v_mul_f32_e32 v16, 0xbfb8aa3b, v29
	v_exp_f32_e32 v16, v16
	s_nop 0
	v_add_f32_e32 v16, 1.0, v16
	v_rcp_f32_e32 v23, v16
	v_lshlrev_b32_e32 v16, 16, v17
	v_and_b32_e32 v17, 0xffff0000, v17
	v_pk_fma_f32 v[18:19], v[22:23], v[18:19], v[20:21]
	s_nop 0
	v_cvt_pk_bf16_f32 v153, v18, v19
	v_mul_f32_e32 v19, 0xbfb8aa3b, v30
	v_mul_f32_e32 v21, 0xbfb8aa3b, v31
	v_exp_f32_e32 v19, v19
	v_exp_f32_e32 v21, v21
	v_lshlrev_b32_e32 v18, 16, v152
	v_add_f32_e32 v19, 1.0, v19
	v_add_f32_e32 v21, 1.0, v21
	v_rcp_f32_e32 v20, v19
	v_rcp_f32_e32 v21, v21
	v_and_b32_e32 v19, 0xffff0000, v152
	v_pk_fma_f32 v[16:17], v[20:21], v[16:17], v[18:19]
	s_nop 0
	v_cvt_pk_bf16_f32 v152, v16, v17
	ds_read2st64_b32 v[16:17], v140 offset0:240 offset1:244
	v_lshlrev_b32_e32 v20, 16, v151
	v_and_b32_e32 v21, 0xffff0000, v151
	s_waitcnt lgkmcnt(0)
	v_lshlrev_b32_e32 v18, 16, v16
	v_and_b32_e32 v19, 0xffff0000, v16
	v_pk_fma_f32 v[0:1], v[0:1], v[18:19], v[20:21]
	v_lshlrev_b32_e32 v16, 16, v150
	v_cvt_pk_bf16_f32 v151, v0, v1
	v_lshlrev_b32_e32 v0, 16, v17
	v_and_b32_e32 v1, 0xffff0000, v17
	v_and_b32_e32 v17, 0xffff0000, v150
	v_pk_fma_f32 v[0:1], v[2:3], v[0:1], v[16:17]
	v_lshlrev_b32_e32 v16, 16, v149
	v_cvt_pk_bf16_f32 v150, v0, v1
	ds_read2st64_b32 v[0:1], v140 offset0:248 offset1:252
	v_and_b32_e32 v17, 0xffff0000, v149
	s_waitcnt lgkmcnt(0)
	v_lshlrev_b32_e32 v2, 16, v0
	v_and_b32_e32 v3, 0xffff0000, v0
	v_mul_f32_e32 v0, 0xbfb8aa3b, v4
	v_exp_f32_e32 v0, v0
	s_nop 0
	v_add_f32_e32 v0, 1.0, v0
	v_rcp_f32_e32 v4, v0
	v_mul_f32_e32 v0, 0xbfb8aa3b, v5
	v_exp_f32_e32 v0, v0
	s_nop 0
	v_add_f32_e32 v0, 1.0, v0
	v_rcp_f32_e32 v5, v0
	v_lshlrev_b32_e32 v0, 16, v1
	v_and_b32_e32 v1, 0xffff0000, v1
	v_pk_fma_f32 v[2:3], v[4:5], v[2:3], v[16:17]
	s_nop 0
	v_cvt_pk_bf16_f32 v149, v2, v3
	v_mul_f32_e32 v3, 0xbfb8aa3b, v6
	v_mul_f32_e32 v5, 0xbfb8aa3b, v7
	v_exp_f32_e32 v3, v3
	v_exp_f32_e32 v5, v5
	v_lshlrev_b32_e32 v2, 16, v148
	v_add_f32_e32 v3, 1.0, v3
	v_add_f32_e32 v5, 1.0, v5
	v_rcp_f32_e32 v4, v3
	v_rcp_f32_e32 v5, v5
	v_and_b32_e32 v3, 0xffff0000, v148
	v_pk_fma_f32 v[0:1], v[4:5], v[0:1], v[2:3]
	s_nop 0
	v_cvt_pk_bf16_f32 v148, v0, v1
	ds_read2st64_b32 v[0:1], v141 offset0:112 offset1:116
	v_lshlrev_b32_e32 v4, 16, v147
	v_and_b32_e32 v5, 0xffff0000, v147
	s_waitcnt lgkmcnt(0)
; DI float sigmf(float x) { return __builtin_amdgcn_rcpf(1.f + __expf(-x)); }
; DI int crow(int i, int h) { return (i & 3) + 8 * (i >> 2) + 4 * h; }
; DI void phase_merge(CP p, const Ptrs& w, int l, bf16_t* sA, bf16_t* sB, unsigned* sU) {
;     ...
; #pragma unroll
;       for (int a = 0; a < 2; ++a)
; #pragma unroll
;         for (int c = 0; c < 2; ++c)
; #pragma unroll
;           for (int i = 0; i < 8; ++i) {
;             unsigned uv = sU[((a * 2 + c) * 8 + i) * 256 + tid];
;             float u0 = __uint_as_float(uv << 16), u1 = __uint_as_float(uv & 0xffff0000u);
;             const unsigned tv = totp[a][c][i];
;             float t0 = __uint_as_float(tv << 16) + sigmf(G[a][c][2 * i]) * u0;
;             float t1 = __uint_as_float(tv & 0xffff0000u) + sigmf(G[a][c][2 * i + 1]) * u1;
;             totp[a][c][i] = pack2(t0, t1);
;           }
;     }
;     bf16_t* dst = w.R2;
; #pragma unroll
;     for (int mi = 0; mi < 2; ++mi)
; #pragma unroll
;       for (int ni = 0; ni < 2; ++ni)
; #pragma unroll
;         for (int i = 0; i < 16; ++i) {
;           int row = m0 + wm * 64 + mi * 32 + crow(i, h), col = n0 + wn * 64 + ni * 32 + r;
;           const unsigned tv = totp[mi][ni][i >> 1];
;           dst[(size_t)row * 2048 + col] = (bf16_t)((i & 1) ? (tv >> 16) : (tv & 0xffffu));
;         }
	v_lshlrev_b32_e32 v2, 16, v0
	v_and_b32_e32 v3, 0xffff0000, v0
	v_mul_f32_e32 v0, 0xbfb8aa3b, v8
	v_exp_f32_e32 v0, v0
	s_nop 0
	v_add_f32_e32 v0, 1.0, v0
	v_rcp_f32_e32 v6, v0
	v_mul_f32_e32 v0, 0xbfb8aa3b, v9
	v_exp_f32_e32 v0, v0
	s_nop 0
	v_add_f32_e32 v0, 1.0, v0
	v_rcp_f32_e32 v7, v0
	v_lshlrev_b32_e32 v0, 16, v1
	v_and_b32_e32 v1, 0xffff0000, v1
	v_pk_fma_f32 v[2:3], v[6:7], v[2:3], v[4:5]
	s_nop 0
	v_cvt_pk_bf16_f32 v147, v2, v3
	v_mul_f32_e32 v3, 0xbfb8aa3b, v10
	v_mul_f32_e32 v5, 0xbfb8aa3b, v11
	v_exp_f32_e32 v3, v3
	v_exp_f32_e32 v5, v5
	v_lshlrev_b32_e32 v2, 16, v146
	v_add_f32_e32 v3, 1.0, v3
	v_add_f32_e32 v5, 1.0, v5
	v_rcp_f32_e32 v4, v3
	v_rcp_f32_e32 v5, v5
	v_and_b32_e32 v3, 0xffff0000, v146
	v_pk_fma_f32 v[0:1], v[4:5], v[0:1], v[2:3]
	s_nop 0
	v_cvt_pk_bf16_f32 v146, v0, v1
	ds_read2st64_b32 v[0:1], v141 offset0:120 offset1:124
	v_lshlrev_b32_e32 v4, 16, v145
	v_and_b32_e32 v5, 0xffff0000, v145
	s_waitcnt lgkmcnt(0)
	v_lshlrev_b32_e32 v2, 16, v0
	v_and_b32_e32 v3, 0xffff0000, v0
	v_mul_f32_e32 v0, 0xbfb8aa3b, v12
	v_exp_f32_e32 v0, v0
	s_nop 0
	v_add_f32_e32 v0, 1.0, v0
	v_rcp_f32_e32 v6, v0
	v_mul_f32_e32 v0, 0xbfb8aa3b, v13
	v_exp_f32_e32 v0, v0
	s_nop 0
	v_add_f32_e32 v0, 1.0, v0
	v_rcp_f32_e32 v7, v0
	v_lshlrev_b32_e32 v0, 16, v1
	v_and_b32_e32 v1, 0xffff0000, v1
	v_pk_fma_f32 v[2:3], v[6:7], v[2:3], v[4:5]
	s_nop 0
	v_cvt_pk_bf16_f32 v145, v2, v3
	v_mul_f32_e32 v3, 0xbfb8aa3b, v14
	v_mul_f32_e32 v5, 0xbfb8aa3b, v15
	v_exp_f32_e32 v3, v3
	v_exp_f32_e32 v5, v5
	v_lshlrev_b32_e32 v2, 16, v144
	v_add_f32_e32 v3, 1.0, v3
	v_add_f32_e32 v5, 1.0, v5
	v_rcp_f32_e32 v4, v3
	v_rcp_f32_e32 v5, v5
	v_and_b32_e32 v3, 0xffff0000, v144
	v_pk_fma_f32 v[0:1], v[4:5], v[0:1], v[2:3]
	s_nop 0
	v_cvt_pk_bf16_f32 v144, v0, v1
	s_cbranch_scc0 .LBB0_871
	v_add_u32_e32 v0, s38, v142
	v_or_b32_e32 v2, s72, v143
	v_or_b32_e32 v6, 1, v0
	v_or_b32_e32 v8, 2, v0
	v_or_b32_e32 v10, 3, v0
	v_or_b32_e32 v12, 8, v0
	v_or_b32_e32 v14, 9, v0
	v_or_b32_e32 v16, 10, v0
	v_or_b32_e32 v18, 11, v0
	v_or_b32_e32 v20, 16, v0
	v_or_b32_e32 v22, 17, v0
	v_or_b32_e32 v24, 18, v0
	v_or_b32_e32 v26, 19, v0
	v_or_b32_e32 v28, 24, v0
	v_or_b32_e32 v30, 25, v0
	v_or_b32_e32 v32, 26, v0
	v_or_b32_e32 v34, 27, v0
	v_ashrrev_i32_e32 v3, 31, v2
	v_ashrrev_i32_e32 v1, 31, v0
	v_ashrrev_i32_e32 v7, 31, v6
	v_ashrrev_i32_e32 v9, 31, v8
	v_ashrrev_i32_e32 v11, 31, v10
	v_ashrrev_i32_e32 v13, 31, v12
	v_ashrrev_i32_e32 v15, 31, v14
	v_ashrrev_i32_e32 v17, 31, v16
	v_ashrrev_i32_e32 v19, 31, v18
	v_ashrrev_i32_e32 v21, 31, v20
	v_ashrrev_i32_e32 v23, 31, v22
	v_ashrrev_i32_e32 v25, 31, v24
	v_ashrrev_i32_e32 v27, 31, v26
	v_ashrrev_i32_e32 v29, 31, v28
	v_ashrrev_i32_e32 v31, 31, v30
	v_ashrrev_i32_e32 v33, 31, v32
	v_ashrrev_i32_e32 v35, 31, v34
	v_lshl_add_u64 v[2:3], v[2:3], 1, s[10:11]
	v_lshlrev_b64 v[4:5], 12, v[0:1]
	v_lshlrev_b64 v[6:7], 12, v[6:7]
	v_lshlrev_b64 v[8:9], 12, v[8:9]
	v_lshlrev_b64 v[10:11], 12, v[10:11]
	v_lshlrev_b64 v[12:13], 12, v[12:13]
	v_lshlrev_b64 v[14:15], 12, v[14:15]
	v_lshlrev_b64 v[16:17], 12, v[16:17]
	v_lshlrev_b64 v[18:19], 12, v[18:19]
	v_lshlrev_b64 v[20:21], 12, v[20:21]
	v_lshlrev_b64 v[22:23], 12, v[22:23]
	v_lshlrev_b64 v[24:25], 12, v[24:25]
	v_lshlrev_b64 v[26:27], 12, v[26:27]
	v_lshlrev_b64 v[28:29], 12, v[28:29]
	v_lshlrev_b64 v[30:31], 12, v[30:31]
	v_lshlrev_b64 v[32:33], 12, v[32:33]
	v_lshlrev_b64 v[34:35], 12, v[34:35]
	v_lshl_add_u64 v[4:5], v[2:3], 0, v[4:5]
	v_lshl_add_u64 v[6:7], v[2:3], 0, v[6:7]
	v_lshl_add_u64 v[8:9], v[2:3], 0, v[8:9]
	v_lshl_add_u64 v[10:11], v[2:3], 0, v[10:11]
	v_lshl_add_u64 v[12:13], v[2:3], 0, v[12:13]
	v_lshl_add_u64 v[14:15], v[2:3], 0, v[14:15]
	v_lshl_add_u64 v[16:17], v[2:3], 0, v[16:17]
	v_lshl_add_u64 v[18:19], v[2:3], 0, v[18:19]
	v_lshl_add_u64 v[20:21], v[2:3], 0, v[20:21]
	v_lshl_add_u64 v[22:23], v[2:3], 0, v[22:23]
	v_lshl_add_u64 v[24:25], v[2:3], 0, v[24:25]
	v_lshl_add_u64 v[26:27], v[2:3], 0, v[26:27]
	v_lshl_add_u64 v[28:29], v[2:3], 0, v[28:29]
	v_lshl_add_u64 v[30:31], v[2:3], 0, v[30:31]
	v_lshl_add_u64 v[32:33], v[2:3], 0, v[32:33]
	v_lshl_add_u64 v[34:35], v[2:3], 0, v[34:35]
	global_store_short v[4:5], v183, off
	global_store_short_d16_hi v[6:7], v183, off
	global_store_short v[8:9], v182, off
	global_store_short_d16_hi v[10:11], v182, off
	global_store_short v[12:13], v181, off
	global_store_short_d16_hi v[14:15], v181, off
	global_store_short v[16:17], v180, off
	global_store_short_d16_hi v[18:19], v180, off
	global_store_short v[20:21], v179, off
	global_store_short_d16_hi v[22:23], v179, off
	global_store_short v[24:25], v177, off
	global_store_short_d16_hi v[26:27], v177, off
	global_store_short v[28:29], v178, off
	global_store_short_d16_hi v[30:31], v178, off
	global_store_short v[32:33], v173, off
; DI int crow(int i, int h) { return (i & 3) + 8 * (i >> 2) + 4 * h; }
; DI void phase_merge(CP p, const Ptrs& w, int l, bf16_t* sA, bf16_t* sB, unsigned* sU) {
;     ...
;     bf16_t* dst = w.R2;
; #pragma unroll
;     for (int mi = 0; mi < 2; ++mi)
; #pragma unroll
;       for (int ni = 0; ni < 2; ++ni)
; #pragma unroll
;         for (int i = 0; i < 16; ++i) {
;           int row = m0 + wm * 64 + mi * 32 + crow(i, h), col = n0 + wn * 64 + ni * 32 + r;
;           const unsigned tv = totp[mi][ni][i >> 1];
;           dst[(size_t)row * 2048 + col] = (bf16_t)((i & 1) ? (tv >> 16) : (tv & 0xffffu));
;         }
;   }
	global_store_short_d16_hi v[34:35], v173, off
	global_store_short v[4:5], v176, off offset:64
	global_store_short_d16_hi v[6:7], v176, off offset:64
	global_store_short v[8:9], v170, off offset:64
	global_store_short_d16_hi v[10:11], v170, off offset:64
	global_store_short v[12:13], v175, off offset:64
	global_store_short_d16_hi v[14:15], v175, off offset:64
	global_store_short v[16:17], v174, off offset:64
	global_store_short_d16_hi v[18:19], v174, off offset:64
	global_store_short v[20:21], v172, off offset:64
	global_store_short_d16_hi v[22:23], v172, off offset:64
	global_store_short v[24:25], v171, off offset:64
	global_store_short_d16_hi v[26:27], v171, off offset:64
	global_store_short v[28:29], v169, off offset:64
	global_store_short_d16_hi v[30:31], v169, off offset:64
	global_store_short v[32:33], v168, off offset:64
	global_store_short_d16_hi v[34:35], v168, off offset:64
	v_or_b32_e32 v4, 32, v0
	v_or_b32_e32 v6, 33, v0
	v_or_b32_e32 v8, 34, v0
	v_or_b32_e32 v10, 35, v0
	v_or_b32_e32 v12, 40, v0
	v_or_b32_e32 v14, 41, v0
	v_or_b32_e32 v16, 42, v0
	v_or_b32_e32 v18, 43, v0
	v_or_b32_e32 v20, 48, v0
	v_or_b32_e32 v22, 49, v0
	v_or_b32_e32 v24, 50, v0
	v_or_b32_e32 v26, 51, v0
	v_or_b32_e32 v28, 56, v0
	v_or_b32_e32 v30, 57, v0
	v_or_b32_e32 v32, 58, v0
	v_or_b32_e32 v0, 59, v0
	v_ashrrev_i32_e32 v5, 31, v4
	v_ashrrev_i32_e32 v7, 31, v6
	v_ashrrev_i32_e32 v9, 31, v8
	v_ashrrev_i32_e32 v11, 31, v10
	v_ashrrev_i32_e32 v13, 31, v12
	v_ashrrev_i32_e32 v15, 31, v14
	v_ashrrev_i32_e32 v17, 31, v16
	v_ashrrev_i32_e32 v19, 31, v18
	v_ashrrev_i32_e32 v21, 31, v20
	v_ashrrev_i32_e32 v23, 31, v22
	v_ashrrev_i32_e32 v25, 31, v24
	v_ashrrev_i32_e32 v27, 31, v26
	v_ashrrev_i32_e32 v29, 31, v28
	v_ashrrev_i32_e32 v31, 31, v30
	v_ashrrev_i32_e32 v33, 31, v32
	v_ashrrev_i32_e32 v1, 31, v0
	v_lshlrev_b64 v[4:5], 12, v[4:5]
	v_lshlrev_b64 v[6:7], 12, v[6:7]
	v_lshlrev_b64 v[8:9], 12, v[8:9]
	v_lshlrev_b64 v[10:11], 12, v[10:11]
	v_lshlrev_b64 v[12:13], 12, v[12:13]
	v_lshlrev_b64 v[14:15], 12, v[14:15]
	v_lshlrev_b64 v[16:17], 12, v[16:17]
	v_lshlrev_b64 v[18:19], 12, v[18:19]
	v_lshlrev_b64 v[20:21], 12, v[20:21]
	v_lshlrev_b64 v[22:23], 12, v[22:23]
	v_lshlrev_b64 v[24:25], 12, v[24:25]
	v_lshlrev_b64 v[26:27], 12, v[26:27]
	v_lshlrev_b64 v[28:29], 12, v[28:29]
	v_lshlrev_b64 v[30:31], 12, v[30:31]
	v_lshlrev_b64 v[32:33], 12, v[32:33]
	v_lshlrev_b64 v[0:1], 12, v[0:1]
	v_lshl_add_u64 v[4:5], v[2:3], 0, v[4:5]
	v_lshl_add_u64 v[6:7], v[2:3], 0, v[6:7]
	v_lshl_add_u64 v[8:9], v[2:3], 0, v[8:9]
	v_lshl_add_u64 v[10:11], v[2:3], 0, v[10:11]
	v_lshl_add_u64 v[12:13], v[2:3], 0, v[12:13]
	v_lshl_add_u64 v[14:15], v[2:3], 0, v[14:15]
	v_lshl_add_u64 v[16:17], v[2:3], 0, v[16:17]
	v_lshl_add_u64 v[18:19], v[2:3], 0, v[18:19]
	v_lshl_add_u64 v[20:21], v[2:3], 0, v[20:21]
	v_lshl_add_u64 v[22:23], v[2:3], 0, v[22:23]
	v_lshl_add_u64 v[24:25], v[2:3], 0, v[24:25]
	v_lshl_add_u64 v[26:27], v[2:3], 0, v[26:27]
	v_lshl_add_u64 v[28:29], v[2:3], 0, v[28:29]
	v_lshl_add_u64 v[30:31], v[2:3], 0, v[30:31]
	v_lshl_add_u64 v[32:33], v[2:3], 0, v[32:33]
	v_lshl_add_u64 v[0:1], v[2:3], 0, v[0:1]
	global_store_short v[4:5], v167, off
	global_store_short_d16_hi v[6:7], v167, off
	global_store_short v[8:9], v164, off
	global_store_short_d16_hi v[10:11], v164, off
	global_store_short v[12:13], v163, off
	global_store_short_d16_hi v[14:15], v163, off
	global_store_short v[16:17], v161, off
	global_store_short_d16_hi v[18:19], v161, off
	global_store_short v[20:21], v155, off
	global_store_short_d16_hi v[22:23], v155, off
	global_store_short v[24:25], v154, off
	global_store_short_d16_hi v[26:27], v154, off
	global_store_short v[28:29], v153, off
	global_store_short_d16_hi v[30:31], v153, off
	global_store_short v[32:33], v152, off
	global_store_short_d16_hi v[0:1], v152, off
	global_store_short v[4:5], v151, off offset:64
	global_store_short_d16_hi v[6:7], v151, off offset:64
	global_store_short v[8:9], v150, off offset:64
	global_store_short_d16_hi v[10:11], v150, off offset:64
	global_store_short v[12:13], v149, off offset:64
	global_store_short_d16_hi v[14:15], v149, off offset:64
	global_store_short v[16:17], v148, off offset:64
	global_store_short_d16_hi v[18:19], v148, off offset:64
	global_store_short v[20:21], v147, off offset:64
	global_store_short_d16_hi v[22:23], v147, off offset:64
	global_store_short v[24:25], v146, off offset:64
	global_store_short_d16_hi v[26:27], v146, off offset:64
	global_store_short v[28:29], v145, off offset:64
	global_store_short_d16_hi v[30:31], v145, off offset:64
	global_store_short v[32:33], v144, off offset:64
	global_store_short_d16_hi v[0:1], v144, off offset:64
	s_add_i32 s69, s69, 1
	s_cmp_lg_u32 s69, s60
	s_mov_b32 s42, s71
	s_cbranch_scc1 .LBB0_861

; DI void gemm_128_deep(const bf16_t* __restrict__ A, int lda, const bf16_t* __restrict__ B, int ldb, int K, f32x16 (&acc)[2][2], bf16_t* sA, bf16_t* sBunused) {
;     ...
;   for (int k0 = 0; k0 < K - 256; k0 += 128) {
;     MMA_TILE(0)
;     ST_LDS(1, qa0, qa1, qa2, qa3, qb0, qb1, qb2, qb3)
;     GL_Q(k0 + 192)
;     __syncthreads();
;     MMA_TILE(1)
;     ST_LDS(0, pa0, pa1, pa2, pa3, pb0, pb1, pb2, pb3)
;     GL_P(k0 + 256)
;     __syncthreads();
;   }
.LBB0_954:
	ds_read_b128 v[152:155], v128
	ds_read_b128 v[168:171], v129 offset:18432
	ds_read_b128 v[172:175], v129 offset:23040
	s_mov_b32 s4, 0x1ba64000
	s_mov_b32 s38, 0x1a064000
	s_mov_b32 s6, 0x1baa4000
	s_waitcnt lgkmcnt(1)
	v_mfma_f32_32x32x16_bf16 v[48:63], v[152:155], v[168:171], v[48:63]
	s_mov_b32 s10, 0x1bac4000
	s_mov_b32 s40, 0x1a084000
	s_mov_b32 s42, 0x1a0a4000
	s_mov_b32 s44, 0x1a0c4000
	s_addk_i32 s47, 0x80
	s_cmpk_lt_u32 s47, 0x680
	s_waitcnt lgkmcnt(0)
	v_mfma_f32_32x32x16_bf16 v[32:47], v[152:155], v[172:175], v[32:47]
	ds_read_b128 v[152:155], v128 offset:4608
	s_waitcnt lgkmcnt(0)
	v_mfma_f32_32x32x16_bf16 v[16:31], v[152:155], v[168:171], v[16:31]
	v_mfma_f32_32x32x16_bf16 v[0:15], v[152:155], v[172:175], v[0:15]
	ds_read_b128 v[152:155], v128 offset:32
	ds_read_b128 v[168:171], v129 offset:18464
	ds_read_b128 v[172:175], v129 offset:23072
	s_waitcnt lgkmcnt(1)
	v_mfma_f32_32x32x16_bf16 v[48:63], v[152:155], v[168:171], v[48:63]
	s_waitcnt lgkmcnt(0)
	v_mfma_f32_32x32x16_bf16 v[32:47], v[152:155], v[172:175], v[32:47]
	ds_read_b128 v[152:155], v128 offset:4640
	s_waitcnt lgkmcnt(0)
	v_mfma_f32_32x32x16_bf16 v[16:31], v[152:155], v[168:171], v[16:31]
	ds_read_b128 v[168:171], v128 offset:64
	v_mfma_f32_32x32x16_bf16 v[0:15], v[152:155], v[172:175], v[0:15]
	ds_read_b128 v[176:179], v128 offset:4672
	ds_read_b128 v[172:175], v129 offset:18496
	ds_read_b128 v[194:197], v129 offset:23104
	ds_read_b128 v[198:201], v128 offset:96
	ds_read_b128 v[202:205], v128 offset:4704
	ds_read_b128 v[206:209], v129 offset:18528
	ds_read_b128 v[210:213], v129 offset:23136
	s_setprio 0
	s_waitcnt vmcnt(15)
	ds_write_b128 v130, v[108:111] offset:36864
	s_waitcnt vmcnt(14)
	ds_write_b128 v130, v[96:99] offset:41472
	s_waitcnt vmcnt(13)
	ds_write_b128 v130, v[100:103] offset:46080
	s_waitcnt vmcnt(12)
	ds_write_b128 v130, v[104:107] offset:50688
	s_waitcnt vmcnt(11)
	ds_write_b128 v130, v[112:115] offset:55296
	s_waitcnt vmcnt(10)
	ds_write_b128 v130, v[116:119] offset:59904
	s_waitcnt vmcnt(9)
	ds_write_b128 v130, v[120:123] offset:64512
	v_lshl_add_u64 v[96:97], v[150:151], 0, v[156:157]
	v_lshl_add_u64 v[98:99], v[148:149], 0, v[156:157]
	v_add_co_u32_e32 v152, vcc, s4, v96
	s_mov_b32 s4, 0x1ba84000
	s_waitcnt lgkmcnt(12)
	v_mfma_f32_32x32x16_bf16 v[48:63], v[168:171], v[172:175], v[48:63]
	s_waitcnt vmcnt(8)
	ds_write_b128 v131, v[124:127] offset:13824
	v_add_co_u32_e64 v154, s[4:5], s4, v96
	v_addc_co_u32_e32 v153, vcc, 0, v97, vcc
	s_nop 0
	v_addc_co_u32_e64 v155, vcc, 0, v97, s[4:5]
	s_waitcnt lgkmcnt(12)
	v_mfma_f32_32x32x16_bf16 v[32:47], v[168:171], v[194:197], v[32:47]
	v_add_co_u32_e64 v168, s[6:7], s6, v96
	v_add_co_u32_e64 v170, s[10:11], s10, v96
	s_nop 0
	v_addc_co_u32_e64 v169, vcc, 0, v97, s[6:7]
	v_addc_co_u32_e64 v171, vcc, 0, v97, s[10:11]
	v_mfma_f32_32x32x16_bf16 v[16:31], v[176:179], v[172:175], v[16:31]
	v_add_co_u32_e64 v172, s[38:39], s38, v98
	v_add_co_u32_e64 v174, s[40:41], s40, v98
	s_nop 0
	v_addc_co_u32_e64 v173, vcc, 0, v99, s[38:39]
	v_addc_co_u32_e64 v175, vcc, 0, v99, s[40:41]
	v_mfma_f32_32x32x16_bf16 v[0:15], v[176:179], v[194:197], v[0:15]
	v_add_co_u32_e64 v176, s[42:43], s42, v98
	v_add_co_u32_e64 v178, s[44:45], s44, v98
	s_nop 0
	v_addc_co_u32_e64 v177, vcc, 0, v99, s[42:43]
	v_addc_co_u32_e64 v179, vcc, 0, v99, s[44:45]
	s_waitcnt lgkmcnt(9)
	v_mfma_f32_32x32x16_bf16 v[48:63], v[198:201], v[206:209], v[48:63]
	global_load_dwordx4 v[108:111], v[152:153], off offset:2176
	global_load_dwordx4 v[96:99], v[154:155], off offset:2176
	global_load_dwordx4 v[100:103], v[168:169], off offset:2176
	global_load_dwordx4 v[104:107], v[170:171], off offset:2176
	global_load_dwordx4 v[112:115], v[172:173], off offset:2176
	global_load_dwordx4 v[116:119], v[174:175], off offset:2176
	global_load_dwordx4 v[120:123], v[176:177], off offset:2176
	global_load_dwordx4 v[124:127], v[178:179], off offset:2176
	s_waitcnt lgkmcnt(0)
	s_barrier
	s_setprio 1
	v_lshl_add_u64 v[148:149], v[148:149], 0, s[94:95]
	v_lshl_add_u64 v[150:151], v[150:151], 0, s[94:95]
	v_mfma_f32_32x32x16_bf16 v[32:47], v[198:201], v[210:213], v[32:47]
	ds_read_b128 v[194:197], v128 offset:36864
	ds_read_b128 v[198:201], v129 offset:55296
	v_mfma_f32_32x32x16_bf16 v[16:31], v[202:205], v[206:209], v[16:31]
	v_mfma_f32_32x32x16_bf16 v[0:15], v[202:205], v[210:213], v[0:15]
	ds_read_b128 v[202:205], v129 offset:59904
	s_waitcnt lgkmcnt(1)
	v_mfma_f32_32x32x16_bf16 v[48:63], v[194:197], v[198:201], v[48:63]
	s_waitcnt lgkmcnt(0)
	v_mfma_f32_32x32x16_bf16 v[32:47], v[194:197], v[202:205], v[32:47]
	ds_read_b128 v[194:197], v128 offset:41472
	s_waitcnt lgkmcnt(0)
	v_mfma_f32_32x32x16_bf16 v[16:31], v[194:197], v[198:201], v[16:31]
	v_mfma_f32_32x32x16_bf16 v[0:15], v[194:197], v[202:205], v[0:15]
	ds_read_b128 v[194:197], v128 offset:36896
	ds_read_b128 v[198:201], v129 offset:55328
	ds_read_b128 v[202:205], v129 offset:59936
	s_waitcnt lgkmcnt(1)
	v_mfma_f32_32x32x16_bf16 v[48:63], v[194:197], v[198:201], v[48:63]
	s_waitcnt lgkmcnt(0)
	v_mfma_f32_32x32x16_bf16 v[32:47], v[194:197], v[202:205], v[32:47]
	ds_read_b128 v[194:197], v128 offset:41504
	s_waitcnt lgkmcnt(0)
	v_mfma_f32_32x32x16_bf16 v[16:31], v[194:197], v[198:201], v[16:31]
	v_mfma_f32_32x32x16_bf16 v[0:15], v[194:197], v[202:205], v[0:15]
	ds_read_b128 v[194:197], v128 offset:36928
	ds_read_b128 v[198:201], v129 offset:55360
	ds_read_b128 v[202:205], v129 offset:59968
	s_waitcnt lgkmcnt(1)
	v_mfma_f32_32x32x16_bf16 v[48:63], v[194:197], v[198:201], v[48:63]
	s_waitcnt lgkmcnt(0)
	v_mfma_f32_32x32x16_bf16 v[32:47], v[194:197], v[202:205], v[32:47]
	ds_read_b128 v[194:197], v128 offset:41536
	s_waitcnt lgkmcnt(0)
	v_mfma_f32_32x32x16_bf16 v[16:31], v[194:197], v[198:201], v[16:31]
	v_mfma_f32_32x32x16_bf16 v[0:15], v[194:197], v[202:205], v[0:15]
	ds_read_b128 v[194:197], v128 offset:36960
	ds_read_b128 v[198:201], v129 offset:55392
	ds_read_b128 v[202:205], v128 offset:41568
	ds_read_b128 v[206:209], v129 offset:60000
	s_setprio 0
	s_waitcnt vmcnt(13)
	ds_write_b128 v130, v[92:95]
	ds_write_b128 v130, v[64:67] offset:4608
	ds_write_b128 v130, v[68:71] offset:9216
	s_waitcnt vmcnt(11)
	ds_write_b128 v130, v[84:87] offset:13824
	ds_write_b128 v130, v[72:75] offset:18432
	s_waitcnt vmcnt(10)
	ds_write_b128 v130, v[76:79] offset:23040
	s_waitcnt vmcnt(9)
	ds_write_b128 v130, v[80:83] offset:27648
	s_waitcnt vmcnt(8)
	ds_write_b128 v130, v[88:91] offset:32256
	global_load_dwordx4 v[92:95], v[152:153], off offset:2304
	global_load_dwordx4 v[64:67], v[154:155], off offset:2304
	global_load_dwordx4 v[68:71], v[168:169], off offset:2304
	global_load_dwordx4 v[84:87], v[170:171], off offset:2304
	global_load_dwordx4 v[72:75], v[172:173], off offset:2304
	global_load_dwordx4 v[76:79], v[174:175], off offset:2304
	global_load_dwordx4 v[80:83], v[176:177], off offset:2304
	global_load_dwordx4 v[88:91], v[178:179], off offset:2304
	s_waitcnt lgkmcnt(0)
	s_barrier
; DI void gemm_128_deep(const bf16_t* __restrict__ A, int lda, const bf16_t* __restrict__ B, int ldb, int K, f32x16 (&acc)[2][2], bf16_t* sA, bf16_t* sBunused) {
;     ...
;   for (int k0 = 0; k0 < K - 256; k0 += 128) {
;     MMA_TILE(0)
;     ST_LDS(1, qa0, qa1, qa2, qa3, qb0, qb1, qb2, qb3)
;     GL_Q(k0 + 192)
;     __syncthreads();
;     MMA_TILE(1)
;     ST_LDS(0, pa0, pa1, pa2, pa3, pb0, pb1, pb2, pb3)
;     GL_P(k0 + 256)
;     __syncthreads();
;   }
;   MMA_TILE(0)
;   ST_LDS(1, qa0, qa1, qa2, qa3, qb0, qb1, qb2, qb3)
;   GL_Q(K - 64)
;   __syncthreads();
;   MMA_TILE(1)
;   ST_LDS(0, pa0, pa1, pa2, pa3, pb0, pb1, pb2, pb3)
;   __syncthreads();
;   MMA_TILE(0)
;   ST_LDS(1, qa0, qa1, qa2, qa3, qb0, qb1, qb2, qb3)
;   __syncthreads();
;   MMA_TILE(1)
;   __syncthreads();
	s_setprio 1
	v_mfma_f32_32x32x16_bf16 v[48:63], v[194:197], v[198:201], v[48:63]
	v_mfma_f32_32x32x16_bf16 v[32:47], v[194:197], v[206:209], v[32:47]
	v_mfma_f32_32x32x16_bf16 v[16:31], v[202:205], v[198:201], v[16:31]
	v_mfma_f32_32x32x16_bf16 v[0:15], v[202:205], v[206:209], v[0:15]
	s_cbranch_scc1 .LBB0_954
	ds_read_b128 v[148:151], v128
	ds_read_b128 v[152:155], v129 offset:18432
	ds_read_b128 v[168:171], v129 offset:23040
	s_mul_hi_i32 s4, s90, 0x3e0f83e1
	s_lshr_b32 s5, s4, 31
	s_ashr_i32 s39, s4, 4
	s_waitcnt lgkmcnt(1)
	v_mfma_f32_32x32x16_bf16 v[48:63], v[148:151], v[152:155], v[48:63]
	s_add_i32 s39, s39, s5
	s_mul_i32 s38, s39, 0x2100
	s_sub_i32 s10, s48, s38
	s_cmpk_lt_i32 s10, 0x100
	s_cselect_b64 s[4:5], -1, 0
	s_and_b64 s[6:7], s[4:5], exec
	s_cselect_b32 s6, 2, s39
	s_waitcnt lgkmcnt(0)
	v_mfma_f32_32x32x16_bf16 v[32:47], v[148:151], v[168:171], v[32:47]
	ds_read_b128 v[148:151], v128 offset:4608
	v_readlane_b32 s7, v254, 56
	s_add_i32 s6, s6, s7
	s_mulk_i32 s6, 0x1800
	s_ashr_i32 s7, s6, 31
	s_lshl_b64 s[6:7], s[6:7], 2
	s_add_u32 s6, s78, s6
	s_waitcnt lgkmcnt(0)
	v_mfma_f32_32x32x16_bf16 v[16:31], v[148:151], v[152:155], v[16:31]
	s_addc_u32 s7, s79, s7
	s_add_u32 s6, s6, 0x4000
	s_addc_u32 s7, s7, 0
	v_readlane_b32 s40, v254, 54
	v_readlane_b32 s41, v254, 55
	s_and_b64 vcc, exec, s[40:41]
	v_mfma_f32_32x32x16_bf16 v[0:15], v[148:151], v[168:171], v[0:15]
	ds_read_b128 v[148:151], v128 offset:32
	ds_read_b128 v[152:155], v129 offset:18464
	ds_read_b128 v[168:171], v129 offset:23072
	s_waitcnt lgkmcnt(1)
	v_mfma_f32_32x32x16_bf16 v[48:63], v[148:151], v[152:155], v[48:63]
	s_waitcnt lgkmcnt(0)
	v_mfma_f32_32x32x16_bf16 v[32:47], v[148:151], v[168:171], v[32:47]
	ds_read_b128 v[148:151], v128 offset:4640
	s_waitcnt lgkmcnt(0)
	v_mfma_f32_32x32x16_bf16 v[16:31], v[148:151], v[152:155], v[16:31]
	v_mfma_f32_32x32x16_bf16 v[0:15], v[148:151], v[168:171], v[0:15]
	ds_read_b128 v[148:151], v128 offset:64
	ds_read_b128 v[152:155], v129 offset:18496
	ds_read_b128 v[168:171], v129 offset:23104
	s_waitcnt lgkmcnt(1)
	v_mfma_f32_32x32x16_bf16 v[48:63], v[148:151], v[152:155], v[48:63]
	s_waitcnt lgkmcnt(0)
	v_mfma_f32_32x32x16_bf16 v[32:47], v[148:151], v[168:171], v[32:47]
	ds_read_b128 v[148:151], v128 offset:4672
	s_waitcnt lgkmcnt(0)
	v_mfma_f32_32x32x16_bf16 v[16:31], v[148:151], v[152:155], v[16:31]
	v_mfma_f32_32x32x16_bf16 v[0:15], v[148:151], v[168:171], v[0:15]
	ds_read_b128 v[148:151], v128 offset:96
	ds_read_b128 v[152:155], v129 offset:18528
	ds_read_b128 v[168:171], v129 offset:23136
	s_waitcnt lgkmcnt(1)
	v_mfma_f32_32x32x16_bf16 v[48:63], v[148:151], v[152:155], v[48:63]
	s_waitcnt lgkmcnt(0)
	v_mfma_f32_32x32x16_bf16 v[32:47], v[148:151], v[168:171], v[32:47]
	ds_read_b128 v[148:151], v128 offset:4704
	s_setprio 0
	s_waitcnt vmcnt(15)
	ds_write_b128 v130, v[108:111] offset:36864
	s_waitcnt vmcnt(14)
	ds_write_b128 v130, v[96:99] offset:41472
	s_waitcnt vmcnt(13)
	ds_write_b128 v130, v[100:103] offset:46080
	s_waitcnt vmcnt(12)
	ds_write_b128 v130, v[104:107] offset:50688
	s_waitcnt vmcnt(11)
	ds_write_b128 v130, v[112:115] offset:55296
	s_waitcnt vmcnt(10)
	ds_write_b128 v130, v[116:119] offset:59904
	s_waitcnt vmcnt(9)
	ds_write_b128 v130, v[120:123] offset:64512
	s_waitcnt vmcnt(8)
	ds_write_b128 v131, v[124:127] offset:13824
	global_load_dwordx4 v[96:99], v[142:143], off offset:3968
	global_load_dwordx4 v[100:103], v[138:139], off offset:3968
	global_load_dwordx4 v[104:107], v[144:145], off offset:3968
	global_load_dwordx4 v[108:111], v[146:147], off offset:3968
	global_load_dwordx4 v[112:115], v[132:133], off offset:3968
	global_load_dwordx4 v[116:119], v[134:135], off offset:3968
	global_load_dwordx4 v[120:123], v[136:137], off offset:3968
	global_load_dwordx4 v[124:127], v[140:141], off offset:3968
	s_waitcnt lgkmcnt(0)
	s_barrier
	s_setprio 1
	ds_read_b128 v[132:135], v128 offset:36864
	ds_read_b128 v[136:139], v129 offset:55296
	ds_read_b128 v[140:143], v129 offset:59904
	s_waitcnt lgkmcnt(1)
	v_mfma_f32_32x32x16_bf16 v[48:63], v[132:135], v[136:139], v[48:63]
	s_waitcnt lgkmcnt(0)
	v_mfma_f32_32x32x16_bf16 v[32:47], v[132:135], v[140:143], v[32:47]
	ds_read_b128 v[132:135], v128 offset:41472
	v_mfma_f32_32x32x16_bf16 v[16:31], v[148:151], v[152:155], v[16:31]
	v_mfma_f32_32x32x16_bf16 v[0:15], v[148:151], v[168:171], v[0:15]
	s_waitcnt lgkmcnt(0)
	v_mfma_f32_32x32x16_bf16 v[16:31], v[132:135], v[136:139], v[16:31]
	v_mfma_f32_32x32x16_bf16 v[0:15], v[132:135], v[140:143], v[0:15]
	ds_read_b128 v[132:135], v128 offset:36896
	ds_read_b128 v[136:139], v129 offset:55328
	ds_read_b128 v[140:143], v129 offset:59936
	s_waitcnt lgkmcnt(1)
	v_mfma_f32_32x32x16_bf16 v[48:63], v[132:135], v[136:139], v[48:63]
	s_waitcnt lgkmcnt(0)
	v_mfma_f32_32x32x16_bf16 v[32:47], v[132:135], v[140:143], v[32:47]
	ds_read_b128 v[132:135], v128 offset:41504
	s_waitcnt lgkmcnt(0)
	v_mfma_f32_32x32x16_bf16 v[16:31], v[132:135], v[136:139], v[16:31]
	v_mfma_f32_32x32x16_bf16 v[0:15], v[132:135], v[140:143], v[0:15]
	ds_read_b128 v[132:135], v128 offset:36928
	ds_read_b128 v[136:139], v129 offset:55360
	ds_read_b128 v[140:143], v129 offset:59968
	s_waitcnt lgkmcnt(1)
	v_mfma_f32_32x32x16_bf16 v[48:63], v[132:135], v[136:139], v[48:63]
	s_waitcnt lgkmcnt(0)
	v_mfma_f32_32x32x16_bf16 v[32:47], v[132:135], v[140:143], v[32:47]
	ds_read_b128 v[132:135], v128 offset:41536
	s_waitcnt lgkmcnt(0)
	v_mfma_f32_32x32x16_bf16 v[16:31], v[132:135], v[136:139], v[16:31]
	v_mfma_f32_32x32x16_bf16 v[0:15], v[132:135], v[140:143], v[0:15]
	ds_read_b128 v[132:135], v128 offset:36960
	ds_read_b128 v[136:139], v129 offset:55392
	ds_read_b128 v[140:143], v129 offset:60000
	s_waitcnt lgkmcnt(1)
	v_mfma_f32_32x32x16_bf16 v[48:63], v[132:135], v[136:139], v[48:63]
	s_waitcnt lgkmcnt(0)
	v_mfma_f32_32x32x16_bf16 v[32:47], v[132:135], v[140:143], v[32:47]
	ds_read_b128 v[132:135], v128 offset:41568
	s_setprio 0
	s_waitcnt vmcnt(15)
	ds_write_b128 v130, v[92:95]
	s_waitcnt vmcnt(14)
	ds_write_b128 v130, v[64:67] offset:4608
	s_waitcnt vmcnt(13)
	ds_write_b128 v130, v[68:71] offset:9216
	s_waitcnt vmcnt(12)
	ds_write_b128 v130, v[84:87] offset:13824
	s_waitcnt vmcnt(11)
	ds_write_b128 v130, v[72:75] offset:18432
	s_waitcnt vmcnt(10)
	ds_write_b128 v130, v[76:79] offset:23040
	s_waitcnt vmcnt(9)
	ds_write_b128 v130, v[80:83] offset:27648
	s_waitcnt vmcnt(8)
	ds_write_b128 v130, v[88:91] offset:32256
	s_waitcnt lgkmcnt(0)
	s_barrier
; DI int crow(int i, int h) { return (i & 3) + 8 * (i >> 2) + 4 * h; }
; DI void gemm_128_deep(const bf16_t* __restrict__ A, int lda, const bf16_t* __restrict__ B, int ldb, int K, f32x16 (&acc)[2][2], bf16_t* sA, bf16_t* sBunused) {
;     ...
;   MMA_TILE(1)
;   ST_LDS(0, pa0, pa1, pa2, pa3, pb0, pb1, pb2, pb3)
;   __syncthreads();
;   MMA_TILE(0)
;   ST_LDS(1, qa0, qa1, qa2, qa3, qb0, qb1, qb2, qb3)
;   __syncthreads();
;   MMA_TILE(1)
;   __syncthreads();
; DI void phase_out(CP p, const Ptrs& w, int l, bf16_t* sA, bf16_t* sB) {
;     ...
;     int b = m0 / TPB, ib = m0 - b * TPB;
;     bool isctx = ib < CTXL;
;     f32x16 acc[2][2];
;     zero_acc(acc);
;     gemm_128_deep(w.R2 + (size_t)m0 * 2048, 2048, out_t + (size_t)n0 * 2048, 2048, 2048, acc, sA, sB);
;     const float* gate = w.mod + (l * 3 + (isctx ? 2 : b)) * 6144 + 4096;
; #pragma unroll
;     for (int mi = 0; mi < 2; ++mi)
; #pragma unroll
;       for (int ni = 0; ni < 2; ++ni) {
;         int col = n0 + wn * 64 + ni * 32 + r;
;         float gt = gate[col];
; #pragma unroll
;         for (int i = 0; i < 16; ++i) {
;           int ii = ib + wm * 64 + mi * 32 + crow(i, h);
;           const float* src = xrow(p, w, l, b * TPB + ii);
;           float* dstp = isctx ? w.xc1 + (size_t)(b * CTXL + ii) * DM : p.out + (size_t)(b * 8192 + ii - CTXL) * DM;
;           dstp[col] = src[col] + gt * acc[mi][ni][i];
	s_setprio 1
	ds_read_b128 v[64:67], v128
	ds_read_b128 v[68:71], v129 offset:18432
	ds_read_b128 v[72:75], v129 offset:23040
	s_waitcnt lgkmcnt(1)
	v_mfma_f32_32x32x16_bf16 v[48:63], v[64:67], v[68:71], v[48:63]
	v_add_u32_e32 v92, s10, v163
	s_mov_b64 s[10:11], -1
	s_waitcnt lgkmcnt(0)
	v_mfma_f32_32x32x16_bf16 v[32:47], v[64:67], v[72:75], v[32:47]
	ds_read_b128 v[64:67], v128 offset:4608
	v_mfma_f32_32x32x16_bf16 v[16:31], v[132:135], v[136:139], v[16:31]
	v_mfma_f32_32x32x16_bf16 v[0:15], v[132:135], v[140:143], v[0:15]
	s_waitcnt lgkmcnt(0)
	v_mfma_f32_32x32x16_bf16 v[16:31], v[64:67], v[68:71], v[16:31]
	v_mfma_f32_32x32x16_bf16 v[0:15], v[64:67], v[72:75], v[0:15]
	ds_read_b128 v[64:67], v128 offset:32
	ds_read_b128 v[68:71], v129 offset:18464
	ds_read_b128 v[72:75], v129 offset:23072
	s_waitcnt lgkmcnt(1)
	v_mfma_f32_32x32x16_bf16 v[48:63], v[64:67], v[68:71], v[48:63]
	s_waitcnt lgkmcnt(0)
	v_mfma_f32_32x32x16_bf16 v[32:47], v[64:67], v[72:75], v[32:47]
	ds_read_b128 v[64:67], v128 offset:4640
	s_waitcnt lgkmcnt(0)
	v_mfma_f32_32x32x16_bf16 v[16:31], v[64:67], v[68:71], v[16:31]
	v_mfma_f32_32x32x16_bf16 v[0:15], v[64:67], v[72:75], v[0:15]
	ds_read_b128 v[64:67], v128 offset:64
	ds_read_b128 v[68:71], v129 offset:18496
	ds_read_b128 v[72:75], v129 offset:23104
	s_waitcnt lgkmcnt(1)
	v_mfma_f32_32x32x16_bf16 v[48:63], v[64:67], v[68:71], v[48:63]
	s_waitcnt lgkmcnt(0)
	v_mfma_f32_32x32x16_bf16 v[32:47], v[64:67], v[72:75], v[32:47]
	ds_read_b128 v[64:67], v128 offset:4672
	s_waitcnt lgkmcnt(0)
	v_mfma_f32_32x32x16_bf16 v[16:31], v[64:67], v[68:71], v[16:31]
	v_mfma_f32_32x32x16_bf16 v[0:15], v[64:67], v[72:75], v[0:15]
	ds_read_b128 v[64:67], v128 offset:96
	ds_read_b128 v[68:71], v129 offset:18528
	ds_read_b128 v[72:75], v129 offset:23136
	s_waitcnt lgkmcnt(1)
	v_mfma_f32_32x32x16_bf16 v[48:63], v[64:67], v[68:71], v[48:63]
	s_waitcnt lgkmcnt(0)
	v_mfma_f32_32x32x16_bf16 v[32:47], v[64:67], v[72:75], v[32:47]
	ds_read_b128 v[64:67], v128 offset:4704
	s_setprio 0
	s_waitcnt vmcnt(7)
	ds_write_b128 v130, v[96:99] offset:36864
	s_waitcnt vmcnt(6)
	ds_write_b128 v130, v[100:103] offset:41472
	s_waitcnt vmcnt(5)
	ds_write_b128 v130, v[104:107] offset:46080
	s_waitcnt vmcnt(4)
	ds_write_b128 v130, v[108:111] offset:50688
	s_waitcnt vmcnt(3)
	ds_write_b128 v130, v[112:115] offset:55296
	s_waitcnt vmcnt(2)
	ds_write_b128 v130, v[116:119] offset:59904
	s_waitcnt vmcnt(1)
	ds_write_b128 v130, v[120:123] offset:64512
	s_waitcnt vmcnt(0)
	ds_write_b128 v131, v[124:127] offset:13824
	s_waitcnt lgkmcnt(0)
	s_barrier
	s_setprio 1
	v_mfma_f32_32x32x16_bf16 v[16:31], v[64:67], v[68:71], v[16:31]
	v_mfma_f32_32x32x16_bf16 v[0:15], v[64:67], v[72:75], v[0:15]
	ds_read_b128 v[64:67], v128 offset:36864
	ds_read_b128 v[68:71], v129 offset:55296
	ds_read_b128 v[72:75], v129 offset:59904
	s_waitcnt lgkmcnt(1)
	v_mfma_f32_32x32x16_bf16 v[48:63], v[64:67], v[68:71], v[48:63]
	s_waitcnt lgkmcnt(0)
	v_mfma_f32_32x32x16_bf16 v[32:47], v[64:67], v[72:75], v[32:47]
	ds_read_b128 v[64:67], v128 offset:41472
	s_waitcnt lgkmcnt(0)
	v_mfma_f32_32x32x16_bf16 v[16:31], v[64:67], v[68:71], v[16:31]
	v_mfma_f32_32x32x16_bf16 v[0:15], v[64:67], v[72:75], v[0:15]
	ds_read_b128 v[64:67], v128 offset:36896
	ds_read_b128 v[68:71], v129 offset:55328
	ds_read_b128 v[72:75], v129 offset:59936
	s_waitcnt lgkmcnt(1)
	v_mfma_f32_32x32x16_bf16 v[48:63], v[64:67], v[68:71], v[48:63]
	s_waitcnt lgkmcnt(0)
	v_mfma_f32_32x32x16_bf16 v[32:47], v[64:67], v[72:75], v[32:47]
	ds_read_b128 v[64:67], v128 offset:41504
	s_waitcnt lgkmcnt(0)
	v_mfma_f32_32x32x16_bf16 v[16:31], v[64:67], v[68:71], v[16:31]
	v_mfma_f32_32x32x16_bf16 v[0:15], v[64:67], v[72:75], v[0:15]
	ds_read_b128 v[64:67], v128 offset:36928
	ds_read_b128 v[68:71], v129 offset:55360
	ds_read_b128 v[72:75], v129 offset:59968
	s_waitcnt lgkmcnt(1)
	v_mfma_f32_32x32x16_bf16 v[48:63], v[64:67], v[68:71], v[48:63]
	s_waitcnt lgkmcnt(0)
	v_mfma_f32_32x32x16_bf16 v[32:47], v[64:67], v[72:75], v[32:47]
	ds_read_b128 v[64:67], v128 offset:41536
	s_waitcnt lgkmcnt(0)
	v_mfma_f32_32x32x16_bf16 v[16:31], v[64:67], v[68:71], v[16:31]
	ds_read_b128 v[68:71], v128 offset:36960
	ds_read_b128 v[76:79], v128 offset:41568
	ds_read_b128 v[80:83], v129 offset:55392
	ds_read_b128 v[84:87], v129 offset:60000
	s_waitcnt lgkmcnt(0)
	s_barrier
	s_setprio 1
	v_mfma_f32_32x32x16_bf16 v[0:15], v[64:67], v[72:75], v[0:15]
	v_or_b32_e32 v64, s46, v161
	v_ashrrev_i32_e32 v65, 31, v64
	v_or_b32_e32 v72, v92, v164
	v_add_u32_e32 v66, s38, v72
	v_mul_hi_i32 v67, v66, s0
	v_mfma_f32_32x32x16_bf16 v[48:63], v[68:71], v[80:83], v[48:63]
	v_mfma_f32_32x32x16_bf16 v[32:47], v[68:71], v[84:87], v[32:47]
	v_lshl_add_u64 v[68:69], v[64:65], 2, s[6:7]
	global_load_dword v90, v[68:69], off
	v_lshrrev_b32_e32 v70, 31, v67
	v_ashrrev_i32_e32 v67, 11, v67
	v_add_u32_e32 v93, v67, v70
	v_mad_i32_i24 v94, v93, s1, v66
	v_cmp_lt_i32_e64 s[42:43], s37, v94
	v_mfma_f32_32x32x16_bf16 v[16:31], v[76:79], v[80:83], v[16:31]
	v_mfma_f32_32x32x16_bf16 v[0:15], v[76:79], v[84:87], v[0:15]
	s_setprio 0
	s_cbranch_vccz .LBB0_961
	s_and_saveexec_b64 s[10:11], s[42:43]
	s_xor_b64 s[10:11], exec, s[10:11]
	v_lshlrev_b32_e32 v66, 13, v93
	s_movk_i32 s40, 0xff00
	v_add3_u32 v66, v66, v94, s40
	s_or_saveexec_b64 s[10:11], s[10:11]
	v_mov_b64_e32 v[70:71], s[76:77]
	s_xor_b64 exec, exec, s[10:11]
	v_lshl_add_u32 v66, v93, 8, v94
	v_mov_b64_e32 v[70:71], s[12:13]
	s_or_b64 exec, exec, s[10:11]
	s_mov_b64 s[10:11], 0
